# hand-written G_UP phase: 256x256 pair tiles sharing the A panel, K-step 32, 4-slot LDS ring, staggered wave halves
# speedup vs baseline: 1.0167x; 1.0167x over previous
.LBB0_42:
	s_add_i32 s0, s50, -1
	s_mul_hi_i32 s1, s0, 0x2e8ba2e9
	s_lshr_b32 s2, s1, 31
	s_ashr_i32 s1, s1, 1
	s_add_i32 s4, s1, s2
	s_mov_b32 s2, s4
	v_writelane_b32 v214, s2, 57
	s_mul_i32 s1, s4, 11
	s_sub_i32 s21, s0, s1
	v_writelane_b32 v214, s3, 58
	s_mov_b64 s[2:3], 0
	s_mov_b64 s[0:1], -1
	s_cmp_lt_i32 s21, 5
	v_writelane_b32 v214, s2, 59
	s_nop 1
	v_writelane_b32 v214, s3, 60
	s_cbranch_scc1 .LBB0_167
	s_cmp_gt_i32 s21, 6
	s_cbranch_scc0 .LBB0_57
	v_readlane_b32 s8, v217, 20
	s_cmp_gt_i32 s21, 7
	v_readlane_b32 s9, v217, 21
	s_cbranch_scc0 .LBB0_58
	s_cmp_gt_i32 s21, 8
	s_cbranch_scc0 .LBB0_59
	s_cmp_eq_u32 s21, 9
	s_cbranch_scc0 .LBB0_71
	v_readlane_b32 s11, v217, 0
	v_readlane_b32 s12, v214, 57
	s_and_b32 s14, s11, 7
	s_lshr_b32 s15, s11, 3
	s_mul_hi_u32 s16, s12, 0x3500000
	s_mul_i32 s12, s12, 0x3500000
	s_add_u32 s40, s48, s12
	s_addc_u32 s41, s49, s16
	s_add_u32 s40, s40, 0x11a4e000
	s_addc_u32 s41, s41, 0
	v_and_b32_e32 v141, 15, v142
	v_lshrrev_b32_e32 v139, 4, v142
	v_and_b32_e32 v139, 3, v139
	v_lshlrev_b32_e32 v140, 6, v141
	v_lshl_add_u32 v140, v139, 4, v140
	v_lshrrev_b32_e32 v139, 3, v141
	v_lshlrev_b32_e32 v139, 5, v139
	v_xor_b32_e32 v135, v140, v139
	v_lshrrev_b32_e32 v139, 7, v142
	v_lshl_add_u32 v134, v139, 12, v135
	v_lshrrev_b32_e32 v139, 6, v142
	v_and_b32_e32 v139, 1, v139
	v_lshl_add_u32 v135, v139, 12, v135
	v_add_u32_e32 v135, 0x4000, v135
	v_and_b32_e32 v141, 63, v142
	v_lshrrev_b32_e32 v139, 2, v141
	v_lshrrev_b32_e32 v140, 6, v142
	v_lshl_add_u32 v139, v140, 4, v139
	v_lshlrev_b32_e32 v139, 11, v139
	v_and_b32_e32 v140, 3, v141
	v_lshlrev_b32_e32 v140, 4, v140
	v_lshrrev_b32_e32 v141, 5, v141
	v_lshlrev_b32_e32 v141, 5, v141
	v_xor_b32_e32 v140, v140, v141
	v_add_u32_e32 v136, v139, v140
	v_add_u32_e32 v137, 0x40000, v136
	v_lshrrev_b32_e32 v139, 7, v142
	v_and_b32_e32 v141, 15, v142
	v_lshl_add_u32 v139, v139, 6, v141
	v_mul_u32_u24_e32 v139, 0x1600, v139
	v_lshrrev_b32_e32 v140, 6, v142
	v_and_b32_e32 v140, 1, v140
	v_lshlrev_b32_e32 v140, 6, v140
	v_lshrrev_b32_e32 v141, 4, v142
	v_and_b32_e32 v141, 3, v141
	v_lshl_add_u32 v140, v141, 3, v140
	v_add_u32_e32 v138, v139, v140
	v_lshrrev_b32_e32 v141, 6, v142
	v_lshlrev_b32_e32 v141, 10, v141
	s_nop 0
	v_readfirstlane_b32 s6, v141
	s_mov_b32 s10, s15
.Lg2_a_item1:
	s_mul_i32 s11, s10, 0x2aab
	s_lshr_b32 s11, s11, 16
	s_mul_i32 s12, s11, 6
	s_sub_u32 s12, s10, s12
	s_mov_b32 s16, 0
	s_and_b32 s17, s14, 3
	s_mul_i32 s17, s17, 6
	s_add_u32 s12, s12, s17
	s_lshl_b32 s12, s12, 8
	s_add_u32 s12, s12, s16
	s_lshr_b32 s17, s14, 2
	s_mul_i32 s17, s17, 22
	s_lshl_b32 s11, s11, 1
	s_add_u32 s11, s11, s17
	s_lshl_b32 s16, s12, 11
	s_add_u32 s0, s24, s16
	s_addc_u32 s1, s25, 0
	s_lshl_b32 s16, s11, 18
	s_add_u32 s2, s40, s16
	s_addc_u32 s3, s41, 0
	s_mul_i32 s16, s12, 0x1600
	s_lshl_b32 s17, s11, 7
	s_add_u32 s16, s16, s17
	s_add_u32 s4, s26, s16
	s_addc_u32 s5, s27, 0
	s_add_u32 m0, s6, 0x0
	s_nop 0
	global_load_lds_dwordx4 v136, s[0:1]
	s_add_u32 m0, s6, 0x2000
	s_nop 0
	global_load_lds_dwordx4 v137, s[0:1]
	s_add_u32 m0, s6, 0x4000
	s_nop 0
	global_load_lds_dwordx4 v136, s[2:3]
	s_add_u32 m0, s6, 0x6000
	s_nop 0
	global_load_lds_dwordx4 v137, s[2:3]
	s_add_u32 s0, s0, 64
	s_addc_u32 s1, s1, 0
	s_add_u32 s2, s2, 64
	s_addc_u32 s3, s3, 0
	s_add_u32 m0, s6, 0x8000
	s_nop 0
	global_load_lds_dwordx4 v136, s[0:1]
	s_add_u32 m0, s6, 0xa000
	s_nop 0
	global_load_lds_dwordx4 v137, s[0:1]
	s_add_u32 m0, s6, 0xc000
	s_nop 0
	global_load_lds_dwordx4 v136, s[2:3]
	s_add_u32 m0, s6, 0xe000
	s_nop 0
	global_load_lds_dwordx4 v137, s[2:3]
	s_add_u32 s0, s0, 64
	s_addc_u32 s1, s1, 0
	s_add_u32 s2, s2, 64
	s_addc_u32 s3, s3, 0
	s_add_u32 m0, s6, 0x10000
	s_nop 0
	global_load_lds_dwordx4 v136, s[0:1]
	s_add_u32 m0, s6, 0x12000
	s_nop 0
	global_load_lds_dwordx4 v137, s[0:1]
	s_add_u32 m0, s6, 0x14000
	s_nop 0
	global_load_lds_dwordx4 v136, s[2:3]
	s_add_u32 m0, s6, 0x16000
	s_nop 0
	global_load_lds_dwordx4 v137, s[2:3]
	s_add_u32 s0, s0, 64
	s_addc_u32 s1, s1, 0
	s_add_u32 s2, s2, 64
	s_addc_u32 s3, s3, 0
	v_mov_b32_e32 v2, 0
	v_mov_b32_e32 v3, 0
	v_mov_b32_e32 v4, 0
	v_mov_b32_e32 v5, 0
	v_mov_b32_e32 v6, 0
	v_mov_b32_e32 v7, 0
	v_mov_b32_e32 v8, 0
	v_mov_b32_e32 v9, 0
	v_mov_b32_e32 v10, 0
	v_mov_b32_e32 v11, 0
	v_mov_b32_e32 v12, 0
	v_mov_b32_e32 v13, 0
	v_mov_b32_e32 v14, 0
	v_mov_b32_e32 v15, 0
	v_mov_b32_e32 v16, 0
	v_mov_b32_e32 v17, 0
	v_mov_b32_e32 v18, 0
	v_mov_b32_e32 v19, 0
	v_mov_b32_e32 v20, 0
	v_mov_b32_e32 v21, 0
	v_mov_b32_e32 v22, 0
	v_mov_b32_e32 v23, 0
	v_mov_b32_e32 v24, 0
	v_mov_b32_e32 v25, 0
	v_mov_b32_e32 v26, 0
	v_mov_b32_e32 v27, 0
	v_mov_b32_e32 v28, 0
	v_mov_b32_e32 v29, 0
	v_mov_b32_e32 v30, 0
	v_mov_b32_e32 v31, 0
	v_mov_b32_e32 v32, 0
	v_mov_b32_e32 v33, 0
	v_mov_b32_e32 v34, 0
	v_mov_b32_e32 v35, 0
	v_mov_b32_e32 v36, 0
	v_mov_b32_e32 v37, 0
	v_mov_b32_e32 v38, 0
	v_mov_b32_e32 v39, 0
	v_mov_b32_e32 v40, 0
	v_mov_b32_e32 v41, 0
	v_mov_b32_e32 v42, 0
	v_mov_b32_e32 v43, 0
	v_mov_b32_e32 v44, 0
	v_mov_b32_e32 v45, 0
	v_mov_b32_e32 v46, 0
	v_mov_b32_e32 v47, 0
	v_mov_b32_e32 v48, 0
	v_mov_b32_e32 v49, 0
	v_mov_b32_e32 v50, 0
	v_mov_b32_e32 v51, 0
	v_mov_b32_e32 v52, 0
	v_mov_b32_e32 v53, 0
	v_mov_b32_e32 v54, 0
	v_mov_b32_e32 v55, 0
	v_mov_b32_e32 v56, 0
	v_mov_b32_e32 v57, 0
	v_mov_b32_e32 v58, 0
	v_mov_b32_e32 v59, 0
	v_mov_b32_e32 v60, 0
	v_mov_b32_e32 v61, 0
	v_mov_b32_e32 v62, 0
	v_mov_b32_e32 v63, 0
	v_mov_b32_e32 v64, 0
	v_mov_b32_e32 v65, 0
	v_mov_b32_e32 v66, 0
	v_mov_b32_e32 v67, 0
	v_mov_b32_e32 v68, 0
	v_mov_b32_e32 v69, 0
	v_mov_b32_e32 v70, 0
	v_mov_b32_e32 v71, 0
	v_mov_b32_e32 v72, 0
	v_mov_b32_e32 v73, 0
	v_mov_b32_e32 v74, 0
	v_mov_b32_e32 v75, 0
	v_mov_b32_e32 v76, 0
	v_mov_b32_e32 v77, 0
	v_mov_b32_e32 v78, 0
	v_mov_b32_e32 v79, 0
	v_mov_b32_e32 v80, 0
	v_mov_b32_e32 v81, 0
	v_mov_b32_e32 v82, 0
	v_mov_b32_e32 v83, 0
	v_mov_b32_e32 v84, 0
	v_mov_b32_e32 v85, 0
	v_mov_b32_e32 v86, 0
	v_mov_b32_e32 v87, 0
	v_mov_b32_e32 v88, 0
	v_mov_b32_e32 v89, 0
	v_mov_b32_e32 v90, 0
	v_mov_b32_e32 v91, 0
	v_mov_b32_e32 v92, 0
	v_mov_b32_e32 v93, 0
	v_mov_b32_e32 v94, 0
	v_mov_b32_e32 v95, 0
	v_mov_b32_e32 v96, 0
	v_mov_b32_e32 v97, 0
	v_mov_b32_e32 v98, 0
	v_mov_b32_e32 v99, 0
	v_mov_b32_e32 v100, 0
	v_mov_b32_e32 v101, 0
	v_mov_b32_e32 v102, 0
	v_mov_b32_e32 v103, 0
	v_mov_b32_e32 v104, 0
	v_mov_b32_e32 v105, 0
	v_mov_b32_e32 v106, 0
	v_mov_b32_e32 v107, 0
	v_mov_b32_e32 v108, 0
	v_mov_b32_e32 v109, 0
	v_mov_b32_e32 v110, 0
	v_mov_b32_e32 v111, 0
	v_mov_b32_e32 v112, 0
	v_mov_b32_e32 v113, 0
	v_mov_b32_e32 v114, 0
	v_mov_b32_e32 v115, 0
	v_mov_b32_e32 v116, 0
	v_mov_b32_e32 v117, 0
	v_mov_b32_e32 v118, 0
	v_mov_b32_e32 v119, 0
	v_mov_b32_e32 v120, 0
	v_mov_b32_e32 v121, 0
	v_mov_b32_e32 v122, 0
	v_mov_b32_e32 v123, 0
	v_mov_b32_e32 v124, 0
	v_mov_b32_e32 v125, 0
	v_mov_b32_e32 v126, 0
	v_mov_b32_e32 v127, 0
	v_mov_b32_e32 v128, 0
	v_mov_b32_e32 v129, 0
	s_bitcmp1_b32 s6, 12
	s_cbranch_scc1 .Lg2_a_grpB2
	s_mov_b32 s7, 7
.Lg2_a_klA4:
	s_waitcnt vmcnt(8)
	s_barrier
	v_add_u32_e32 v139, 0x0, v134
	v_add_u32_e32 v140, 0x0, v135
	ds_read_b128 v[162:165], v139 offset:0
	ds_read_b128 v[166:169], v139 offset:1024
	ds_read_b128 v[170:173], v139 offset:2048
	ds_read_b128 v[174:177], v139 offset:3072
	ds_read_b128 v[194:197], v140 offset:0
	ds_read_b128 v[198:201], v140 offset:1024
	ds_read_b128 v[202:205], v140 offset:2048
	ds_read_b128 v[206:209], v140 offset:3072
	ds_read_b128 v[218:221], v140 offset:8192
	ds_read_b128 v[222:225], v140 offset:9216
	ds_read_b128 v[226:229], v140 offset:10240
	ds_read_b128 v[230:233], v140 offset:11264
	s_add_u32 m0, s6, 0x18000
	s_nop 0
	global_load_lds_dwordx4 v136, s[0:1]
	s_add_u32 m0, s6, 0x1a000
	s_nop 0
	global_load_lds_dwordx4 v137, s[0:1]
	s_add_u32 m0, s6, 0x1c000
	s_nop 0
	global_load_lds_dwordx4 v136, s[2:3]
	s_add_u32 m0, s6, 0x1e000
	s_nop 0
	global_load_lds_dwordx4 v137, s[2:3]
	s_add_u32 s0, s0, 64
	s_addc_u32 s1, s1, 0
	s_add_u32 s2, s2, 64
	s_addc_u32 s3, s3, 0
	s_waitcnt lgkmcnt(4)
	v_mfma_f32_16x16x32_bf16 v[2:5], v[194:197], v[162:165], v[2:5]
	v_mfma_f32_16x16x32_bf16 v[6:9], v[198:201], v[162:165], v[6:9]
	v_mfma_f32_16x16x32_bf16 v[10:13], v[202:205], v[162:165], v[10:13]
	v_mfma_f32_16x16x32_bf16 v[14:17], v[206:209], v[162:165], v[14:17]
	v_mfma_f32_16x16x32_bf16 v[18:21], v[194:197], v[166:169], v[18:21]
	v_mfma_f32_16x16x32_bf16 v[22:25], v[198:201], v[166:169], v[22:25]
	v_mfma_f32_16x16x32_bf16 v[26:29], v[202:205], v[166:169], v[26:29]
	v_mfma_f32_16x16x32_bf16 v[30:33], v[206:209], v[166:169], v[30:33]
	v_mfma_f32_16x16x32_bf16 v[34:37], v[194:197], v[170:173], v[34:37]
	v_mfma_f32_16x16x32_bf16 v[38:41], v[198:201], v[170:173], v[38:41]
	v_mfma_f32_16x16x32_bf16 v[42:45], v[202:205], v[170:173], v[42:45]
	v_mfma_f32_16x16x32_bf16 v[46:49], v[206:209], v[170:173], v[46:49]
	v_mfma_f32_16x16x32_bf16 v[50:53], v[194:197], v[174:177], v[50:53]
	v_mfma_f32_16x16x32_bf16 v[54:57], v[198:201], v[174:177], v[54:57]
	v_mfma_f32_16x16x32_bf16 v[58:61], v[202:205], v[174:177], v[58:61]
	v_mfma_f32_16x16x32_bf16 v[62:65], v[206:209], v[174:177], v[62:65]
	s_waitcnt lgkmcnt(0)
	v_mfma_f32_16x16x32_bf16 v[66:69], v[218:221], v[162:165], v[66:69]
	v_mfma_f32_16x16x32_bf16 v[70:73], v[222:225], v[162:165], v[70:73]
	v_mfma_f32_16x16x32_bf16 v[74:77], v[226:229], v[162:165], v[74:77]
	v_mfma_f32_16x16x32_bf16 v[78:81], v[230:233], v[162:165], v[78:81]
	v_mfma_f32_16x16x32_bf16 v[82:85], v[218:221], v[166:169], v[82:85]
	v_mfma_f32_16x16x32_bf16 v[86:89], v[222:225], v[166:169], v[86:89]
	v_mfma_f32_16x16x32_bf16 v[90:93], v[226:229], v[166:169], v[90:93]
	v_mfma_f32_16x16x32_bf16 v[94:97], v[230:233], v[166:169], v[94:97]
	v_mfma_f32_16x16x32_bf16 v[98:101], v[218:221], v[170:173], v[98:101]
	v_mfma_f32_16x16x32_bf16 v[102:105], v[222:225], v[170:173], v[102:105]
	v_mfma_f32_16x16x32_bf16 v[106:109], v[226:229], v[170:173], v[106:109]
	v_mfma_f32_16x16x32_bf16 v[110:113], v[230:233], v[170:173], v[110:113]
	v_mfma_f32_16x16x32_bf16 v[114:117], v[218:221], v[174:177], v[114:117]
	v_mfma_f32_16x16x32_bf16 v[118:121], v[222:225], v[174:177], v[118:121]
	v_mfma_f32_16x16x32_bf16 v[122:125], v[226:229], v[174:177], v[122:125]
	v_mfma_f32_16x16x32_bf16 v[126:129], v[230:233], v[174:177], v[126:129]
	s_waitcnt vmcnt(8)
	s_barrier
	v_add_u32_e32 v139, 0x8000, v134
	v_add_u32_e32 v140, 0x8000, v135
	ds_read_b128 v[162:165], v139 offset:0
	ds_read_b128 v[166:169], v139 offset:1024
	ds_read_b128 v[170:173], v139 offset:2048
	ds_read_b128 v[174:177], v139 offset:3072
	ds_read_b128 v[194:197], v140 offset:0
	ds_read_b128 v[198:201], v140 offset:1024
	ds_read_b128 v[202:205], v140 offset:2048
	ds_read_b128 v[206:209], v140 offset:3072
	ds_read_b128 v[218:221], v140 offset:8192
	ds_read_b128 v[222:225], v140 offset:9216
	ds_read_b128 v[226:229], v140 offset:10240
	ds_read_b128 v[230:233], v140 offset:11264
	s_add_u32 m0, s6, 0x0
	s_nop 0
	global_load_lds_dwordx4 v136, s[0:1]
	s_add_u32 m0, s6, 0x2000
	s_nop 0
	global_load_lds_dwordx4 v137, s[0:1]
	s_add_u32 m0, s6, 0x4000
	s_nop 0
	global_load_lds_dwordx4 v136, s[2:3]
	s_add_u32 m0, s6, 0x6000
	s_nop 0
	global_load_lds_dwordx4 v137, s[2:3]
	s_add_u32 s0, s0, 64
	s_addc_u32 s1, s1, 0
	s_add_u32 s2, s2, 64
	s_addc_u32 s3, s3, 0
	s_waitcnt lgkmcnt(4)
	v_mfma_f32_16x16x32_bf16 v[2:5], v[194:197], v[162:165], v[2:5]
	v_mfma_f32_16x16x32_bf16 v[6:9], v[198:201], v[162:165], v[6:9]
	v_mfma_f32_16x16x32_bf16 v[10:13], v[202:205], v[162:165], v[10:13]
	v_mfma_f32_16x16x32_bf16 v[14:17], v[206:209], v[162:165], v[14:17]
	v_mfma_f32_16x16x32_bf16 v[18:21], v[194:197], v[166:169], v[18:21]
	v_mfma_f32_16x16x32_bf16 v[22:25], v[198:201], v[166:169], v[22:25]
	v_mfma_f32_16x16x32_bf16 v[26:29], v[202:205], v[166:169], v[26:29]
	v_mfma_f32_16x16x32_bf16 v[30:33], v[206:209], v[166:169], v[30:33]
	v_mfma_f32_16x16x32_bf16 v[34:37], v[194:197], v[170:173], v[34:37]
	v_mfma_f32_16x16x32_bf16 v[38:41], v[198:201], v[170:173], v[38:41]
	v_mfma_f32_16x16x32_bf16 v[42:45], v[202:205], v[170:173], v[42:45]
	v_mfma_f32_16x16x32_bf16 v[46:49], v[206:209], v[170:173], v[46:49]
	v_mfma_f32_16x16x32_bf16 v[50:53], v[194:197], v[174:177], v[50:53]
	v_mfma_f32_16x16x32_bf16 v[54:57], v[198:201], v[174:177], v[54:57]
	v_mfma_f32_16x16x32_bf16 v[58:61], v[202:205], v[174:177], v[58:61]
	v_mfma_f32_16x16x32_bf16 v[62:65], v[206:209], v[174:177], v[62:65]
	s_waitcnt lgkmcnt(0)
	v_mfma_f32_16x16x32_bf16 v[66:69], v[218:221], v[162:165], v[66:69]
	v_mfma_f32_16x16x32_bf16 v[70:73], v[222:225], v[162:165], v[70:73]
	v_mfma_f32_16x16x32_bf16 v[74:77], v[226:229], v[162:165], v[74:77]
	v_mfma_f32_16x16x32_bf16 v[78:81], v[230:233], v[162:165], v[78:81]
	v_mfma_f32_16x16x32_bf16 v[82:85], v[218:221], v[166:169], v[82:85]
	v_mfma_f32_16x16x32_bf16 v[86:89], v[222:225], v[166:169], v[86:89]
	v_mfma_f32_16x16x32_bf16 v[90:93], v[226:229], v[166:169], v[90:93]
	v_mfma_f32_16x16x32_bf16 v[94:97], v[230:233], v[166:169], v[94:97]
	v_mfma_f32_16x16x32_bf16 v[98:101], v[218:221], v[170:173], v[98:101]
	v_mfma_f32_16x16x32_bf16 v[102:105], v[222:225], v[170:173], v[102:105]
	v_mfma_f32_16x16x32_bf16 v[106:109], v[226:229], v[170:173], v[106:109]
	v_mfma_f32_16x16x32_bf16 v[110:113], v[230:233], v[170:173], v[110:113]
	v_mfma_f32_16x16x32_bf16 v[114:117], v[218:221], v[174:177], v[114:117]
	v_mfma_f32_16x16x32_bf16 v[118:121], v[222:225], v[174:177], v[118:121]
	v_mfma_f32_16x16x32_bf16 v[122:125], v[226:229], v[174:177], v[122:125]
	v_mfma_f32_16x16x32_bf16 v[126:129], v[230:233], v[174:177], v[126:129]
	s_waitcnt vmcnt(8)
	s_barrier
	v_add_u32_e32 v139, 0x10000, v134
	v_add_u32_e32 v140, 0x10000, v135
	ds_read_b128 v[162:165], v139 offset:0
	ds_read_b128 v[166:169], v139 offset:1024
	ds_read_b128 v[170:173], v139 offset:2048
	ds_read_b128 v[174:177], v139 offset:3072
	ds_read_b128 v[194:197], v140 offset:0
	ds_read_b128 v[198:201], v140 offset:1024
	ds_read_b128 v[202:205], v140 offset:2048
	ds_read_b128 v[206:209], v140 offset:3072
	ds_read_b128 v[218:221], v140 offset:8192
	ds_read_b128 v[222:225], v140 offset:9216
	ds_read_b128 v[226:229], v140 offset:10240
	ds_read_b128 v[230:233], v140 offset:11264
	s_add_u32 m0, s6, 0x8000
	s_nop 0
	global_load_lds_dwordx4 v136, s[0:1]
	s_add_u32 m0, s6, 0xa000
	s_nop 0
	global_load_lds_dwordx4 v137, s[0:1]
	s_add_u32 m0, s6, 0xc000
	s_nop 0
	global_load_lds_dwordx4 v136, s[2:3]
	s_add_u32 m0, s6, 0xe000
	s_nop 0
	global_load_lds_dwordx4 v137, s[2:3]
	s_add_u32 s0, s0, 64
	s_addc_u32 s1, s1, 0
	s_add_u32 s2, s2, 64
	s_addc_u32 s3, s3, 0
	s_waitcnt lgkmcnt(4)
	v_mfma_f32_16x16x32_bf16 v[2:5], v[194:197], v[162:165], v[2:5]
	v_mfma_f32_16x16x32_bf16 v[6:9], v[198:201], v[162:165], v[6:9]
	v_mfma_f32_16x16x32_bf16 v[10:13], v[202:205], v[162:165], v[10:13]
	v_mfma_f32_16x16x32_bf16 v[14:17], v[206:209], v[162:165], v[14:17]
	v_mfma_f32_16x16x32_bf16 v[18:21], v[194:197], v[166:169], v[18:21]
	v_mfma_f32_16x16x32_bf16 v[22:25], v[198:201], v[166:169], v[22:25]
	v_mfma_f32_16x16x32_bf16 v[26:29], v[202:205], v[166:169], v[26:29]
	v_mfma_f32_16x16x32_bf16 v[30:33], v[206:209], v[166:169], v[30:33]
	v_mfma_f32_16x16x32_bf16 v[34:37], v[194:197], v[170:173], v[34:37]
	v_mfma_f32_16x16x32_bf16 v[38:41], v[198:201], v[170:173], v[38:41]
	v_mfma_f32_16x16x32_bf16 v[42:45], v[202:205], v[170:173], v[42:45]
	v_mfma_f32_16x16x32_bf16 v[46:49], v[206:209], v[170:173], v[46:49]
	v_mfma_f32_16x16x32_bf16 v[50:53], v[194:197], v[174:177], v[50:53]
	v_mfma_f32_16x16x32_bf16 v[54:57], v[198:201], v[174:177], v[54:57]
	v_mfma_f32_16x16x32_bf16 v[58:61], v[202:205], v[174:177], v[58:61]
	v_mfma_f32_16x16x32_bf16 v[62:65], v[206:209], v[174:177], v[62:65]
	s_waitcnt lgkmcnt(0)
	v_mfma_f32_16x16x32_bf16 v[66:69], v[218:221], v[162:165], v[66:69]
	v_mfma_f32_16x16x32_bf16 v[70:73], v[222:225], v[162:165], v[70:73]
	v_mfma_f32_16x16x32_bf16 v[74:77], v[226:229], v[162:165], v[74:77]
	v_mfma_f32_16x16x32_bf16 v[78:81], v[230:233], v[162:165], v[78:81]
	v_mfma_f32_16x16x32_bf16 v[82:85], v[218:221], v[166:169], v[82:85]
	v_mfma_f32_16x16x32_bf16 v[86:89], v[222:225], v[166:169], v[86:89]
	v_mfma_f32_16x16x32_bf16 v[90:93], v[226:229], v[166:169], v[90:93]
	v_mfma_f32_16x16x32_bf16 v[94:97], v[230:233], v[166:169], v[94:97]
	v_mfma_f32_16x16x32_bf16 v[98:101], v[218:221], v[170:173], v[98:101]
	v_mfma_f32_16x16x32_bf16 v[102:105], v[222:225], v[170:173], v[102:105]
	v_mfma_f32_16x16x32_bf16 v[106:109], v[226:229], v[170:173], v[106:109]
	v_mfma_f32_16x16x32_bf16 v[110:113], v[230:233], v[170:173], v[110:113]
	v_mfma_f32_16x16x32_bf16 v[114:117], v[218:221], v[174:177], v[114:117]
	v_mfma_f32_16x16x32_bf16 v[118:121], v[222:225], v[174:177], v[118:121]
	v_mfma_f32_16x16x32_bf16 v[122:125], v[226:229], v[174:177], v[122:125]
	v_mfma_f32_16x16x32_bf16 v[126:129], v[230:233], v[174:177], v[126:129]
	s_waitcnt vmcnt(8)
	s_barrier
	v_add_u32_e32 v139, 0x18000, v134
	v_add_u32_e32 v140, 0x18000, v135
	ds_read_b128 v[162:165], v139 offset:0
	ds_read_b128 v[166:169], v139 offset:1024
	ds_read_b128 v[170:173], v139 offset:2048
	ds_read_b128 v[174:177], v139 offset:3072
	ds_read_b128 v[194:197], v140 offset:0
	ds_read_b128 v[198:201], v140 offset:1024
	ds_read_b128 v[202:205], v140 offset:2048
	ds_read_b128 v[206:209], v140 offset:3072
	ds_read_b128 v[218:221], v140 offset:8192
	ds_read_b128 v[222:225], v140 offset:9216
	ds_read_b128 v[226:229], v140 offset:10240
	ds_read_b128 v[230:233], v140 offset:11264
	s_add_u32 m0, s6, 0x10000
	s_nop 0
	global_load_lds_dwordx4 v136, s[0:1]
	s_add_u32 m0, s6, 0x12000
	s_nop 0
	global_load_lds_dwordx4 v137, s[0:1]
	s_add_u32 m0, s6, 0x14000
	s_nop 0
	global_load_lds_dwordx4 v136, s[2:3]
	s_add_u32 m0, s6, 0x16000
	s_nop 0
	global_load_lds_dwordx4 v137, s[2:3]
	s_add_u32 s0, s0, 64
	s_addc_u32 s1, s1, 0
	s_add_u32 s2, s2, 64
	s_addc_u32 s3, s3, 0
	s_waitcnt lgkmcnt(4)
	v_mfma_f32_16x16x32_bf16 v[2:5], v[194:197], v[162:165], v[2:5]
	v_mfma_f32_16x16x32_bf16 v[6:9], v[198:201], v[162:165], v[6:9]
	v_mfma_f32_16x16x32_bf16 v[10:13], v[202:205], v[162:165], v[10:13]
	v_mfma_f32_16x16x32_bf16 v[14:17], v[206:209], v[162:165], v[14:17]
	v_mfma_f32_16x16x32_bf16 v[18:21], v[194:197], v[166:169], v[18:21]
	v_mfma_f32_16x16x32_bf16 v[22:25], v[198:201], v[166:169], v[22:25]
	v_mfma_f32_16x16x32_bf16 v[26:29], v[202:205], v[166:169], v[26:29]
	v_mfma_f32_16x16x32_bf16 v[30:33], v[206:209], v[166:169], v[30:33]
	v_mfma_f32_16x16x32_bf16 v[34:37], v[194:197], v[170:173], v[34:37]
	v_mfma_f32_16x16x32_bf16 v[38:41], v[198:201], v[170:173], v[38:41]
	v_mfma_f32_16x16x32_bf16 v[42:45], v[202:205], v[170:173], v[42:45]
	v_mfma_f32_16x16x32_bf16 v[46:49], v[206:209], v[170:173], v[46:49]
	v_mfma_f32_16x16x32_bf16 v[50:53], v[194:197], v[174:177], v[50:53]
	v_mfma_f32_16x16x32_bf16 v[54:57], v[198:201], v[174:177], v[54:57]
	v_mfma_f32_16x16x32_bf16 v[58:61], v[202:205], v[174:177], v[58:61]
	v_mfma_f32_16x16x32_bf16 v[62:65], v[206:209], v[174:177], v[62:65]
	s_waitcnt lgkmcnt(0)
	v_mfma_f32_16x16x32_bf16 v[66:69], v[218:221], v[162:165], v[66:69]
	v_mfma_f32_16x16x32_bf16 v[70:73], v[222:225], v[162:165], v[70:73]
	v_mfma_f32_16x16x32_bf16 v[74:77], v[226:229], v[162:165], v[74:77]
	v_mfma_f32_16x16x32_bf16 v[78:81], v[230:233], v[162:165], v[78:81]
	v_mfma_f32_16x16x32_bf16 v[82:85], v[218:221], v[166:169], v[82:85]
	v_mfma_f32_16x16x32_bf16 v[86:89], v[222:225], v[166:169], v[86:89]
	v_mfma_f32_16x16x32_bf16 v[90:93], v[226:229], v[166:169], v[90:93]
	v_mfma_f32_16x16x32_bf16 v[94:97], v[230:233], v[166:169], v[94:97]
	v_mfma_f32_16x16x32_bf16 v[98:101], v[218:221], v[170:173], v[98:101]
	v_mfma_f32_16x16x32_bf16 v[102:105], v[222:225], v[170:173], v[102:105]
	v_mfma_f32_16x16x32_bf16 v[106:109], v[226:229], v[170:173], v[106:109]
	v_mfma_f32_16x16x32_bf16 v[110:113], v[230:233], v[170:173], v[110:113]
	v_mfma_f32_16x16x32_bf16 v[114:117], v[218:221], v[174:177], v[114:117]
	v_mfma_f32_16x16x32_bf16 v[118:121], v[222:225], v[174:177], v[118:121]
	v_mfma_f32_16x16x32_bf16 v[122:125], v[226:229], v[174:177], v[122:125]
	v_mfma_f32_16x16x32_bf16 v[126:129], v[230:233], v[174:177], v[126:129]
	s_sub_u32 s7, s7, 1
	s_cmp_lg_u32 s7, 0
	s_cbranch_scc1 .Lg2_a_klA4
	s_waitcnt vmcnt(8)
	s_barrier
	v_add_u32_e32 v139, 0x0, v134
	v_add_u32_e32 v140, 0x0, v135
	ds_read_b128 v[162:165], v139 offset:0
	ds_read_b128 v[166:169], v139 offset:1024
	ds_read_b128 v[170:173], v139 offset:2048
	ds_read_b128 v[174:177], v139 offset:3072
	ds_read_b128 v[194:197], v140 offset:0
	ds_read_b128 v[198:201], v140 offset:1024
	ds_read_b128 v[202:205], v140 offset:2048
	ds_read_b128 v[206:209], v140 offset:3072
	ds_read_b128 v[218:221], v140 offset:8192
	ds_read_b128 v[222:225], v140 offset:9216
	ds_read_b128 v[226:229], v140 offset:10240
	ds_read_b128 v[230:233], v140 offset:11264
	s_add_u32 m0, s6, 0x18000
	s_nop 0
	global_load_lds_dwordx4 v136, s[0:1]
	s_add_u32 m0, s6, 0x1a000
	s_nop 0
	global_load_lds_dwordx4 v137, s[0:1]
	s_add_u32 m0, s6, 0x1c000
	s_nop 0
	global_load_lds_dwordx4 v136, s[2:3]
	s_add_u32 m0, s6, 0x1e000
	s_nop 0
	global_load_lds_dwordx4 v137, s[2:3]
	s_add_u32 s0, s0, 64
	s_addc_u32 s1, s1, 0
	s_add_u32 s2, s2, 64
	s_addc_u32 s3, s3, 0
	s_waitcnt lgkmcnt(4)
	v_mfma_f32_16x16x32_bf16 v[2:5], v[194:197], v[162:165], v[2:5]
	v_mfma_f32_16x16x32_bf16 v[6:9], v[198:201], v[162:165], v[6:9]
	v_mfma_f32_16x16x32_bf16 v[10:13], v[202:205], v[162:165], v[10:13]
	v_mfma_f32_16x16x32_bf16 v[14:17], v[206:209], v[162:165], v[14:17]
	v_mfma_f32_16x16x32_bf16 v[18:21], v[194:197], v[166:169], v[18:21]
	v_mfma_f32_16x16x32_bf16 v[22:25], v[198:201], v[166:169], v[22:25]
	v_mfma_f32_16x16x32_bf16 v[26:29], v[202:205], v[166:169], v[26:29]
	v_mfma_f32_16x16x32_bf16 v[30:33], v[206:209], v[166:169], v[30:33]
	v_mfma_f32_16x16x32_bf16 v[34:37], v[194:197], v[170:173], v[34:37]
	v_mfma_f32_16x16x32_bf16 v[38:41], v[198:201], v[170:173], v[38:41]
	v_mfma_f32_16x16x32_bf16 v[42:45], v[202:205], v[170:173], v[42:45]
	v_mfma_f32_16x16x32_bf16 v[46:49], v[206:209], v[170:173], v[46:49]
	v_mfma_f32_16x16x32_bf16 v[50:53], v[194:197], v[174:177], v[50:53]
	v_mfma_f32_16x16x32_bf16 v[54:57], v[198:201], v[174:177], v[54:57]
	v_mfma_f32_16x16x32_bf16 v[58:61], v[202:205], v[174:177], v[58:61]
	v_mfma_f32_16x16x32_bf16 v[62:65], v[206:209], v[174:177], v[62:65]
	s_waitcnt lgkmcnt(0)
	v_mfma_f32_16x16x32_bf16 v[66:69], v[218:221], v[162:165], v[66:69]
	v_mfma_f32_16x16x32_bf16 v[70:73], v[222:225], v[162:165], v[70:73]
	v_mfma_f32_16x16x32_bf16 v[74:77], v[226:229], v[162:165], v[74:77]
	v_mfma_f32_16x16x32_bf16 v[78:81], v[230:233], v[162:165], v[78:81]
	v_mfma_f32_16x16x32_bf16 v[82:85], v[218:221], v[166:169], v[82:85]
	v_mfma_f32_16x16x32_bf16 v[86:89], v[222:225], v[166:169], v[86:89]
	v_mfma_f32_16x16x32_bf16 v[90:93], v[226:229], v[166:169], v[90:93]
	v_mfma_f32_16x16x32_bf16 v[94:97], v[230:233], v[166:169], v[94:97]
	v_mfma_f32_16x16x32_bf16 v[98:101], v[218:221], v[170:173], v[98:101]
	v_mfma_f32_16x16x32_bf16 v[102:105], v[222:225], v[170:173], v[102:105]
	v_mfma_f32_16x16x32_bf16 v[106:109], v[226:229], v[170:173], v[106:109]
	v_mfma_f32_16x16x32_bf16 v[110:113], v[230:233], v[170:173], v[110:113]
	v_mfma_f32_16x16x32_bf16 v[114:117], v[218:221], v[174:177], v[114:117]
	v_mfma_f32_16x16x32_bf16 v[118:121], v[222:225], v[174:177], v[118:121]
	v_mfma_f32_16x16x32_bf16 v[122:125], v[226:229], v[174:177], v[122:125]
	v_mfma_f32_16x16x32_bf16 v[126:129], v[230:233], v[174:177], v[126:129]
	s_waitcnt vmcnt(8)
	s_barrier
	v_add_u32_e32 v139, 0x8000, v134
	v_add_u32_e32 v140, 0x8000, v135
	ds_read_b128 v[162:165], v139 offset:0
	ds_read_b128 v[166:169], v139 offset:1024
	ds_read_b128 v[170:173], v139 offset:2048
	ds_read_b128 v[174:177], v139 offset:3072
	ds_read_b128 v[194:197], v140 offset:0
	ds_read_b128 v[198:201], v140 offset:1024
	ds_read_b128 v[202:205], v140 offset:2048
	ds_read_b128 v[206:209], v140 offset:3072
	ds_read_b128 v[218:221], v140 offset:8192
	ds_read_b128 v[222:225], v140 offset:9216
	ds_read_b128 v[226:229], v140 offset:10240
	ds_read_b128 v[230:233], v140 offset:11264
	s_waitcnt lgkmcnt(4)
	v_mfma_f32_16x16x32_bf16 v[2:5], v[194:197], v[162:165], v[2:5]
	v_mfma_f32_16x16x32_bf16 v[6:9], v[198:201], v[162:165], v[6:9]
	v_mfma_f32_16x16x32_bf16 v[10:13], v[202:205], v[162:165], v[10:13]
	v_mfma_f32_16x16x32_bf16 v[14:17], v[206:209], v[162:165], v[14:17]
	v_mfma_f32_16x16x32_bf16 v[18:21], v[194:197], v[166:169], v[18:21]
	v_mfma_f32_16x16x32_bf16 v[22:25], v[198:201], v[166:169], v[22:25]
	v_mfma_f32_16x16x32_bf16 v[26:29], v[202:205], v[166:169], v[26:29]
	v_mfma_f32_16x16x32_bf16 v[30:33], v[206:209], v[166:169], v[30:33]
	v_mfma_f32_16x16x32_bf16 v[34:37], v[194:197], v[170:173], v[34:37]
	v_mfma_f32_16x16x32_bf16 v[38:41], v[198:201], v[170:173], v[38:41]
	v_mfma_f32_16x16x32_bf16 v[42:45], v[202:205], v[170:173], v[42:45]
	v_mfma_f32_16x16x32_bf16 v[46:49], v[206:209], v[170:173], v[46:49]
	v_mfma_f32_16x16x32_bf16 v[50:53], v[194:197], v[174:177], v[50:53]
	v_mfma_f32_16x16x32_bf16 v[54:57], v[198:201], v[174:177], v[54:57]
	v_mfma_f32_16x16x32_bf16 v[58:61], v[202:205], v[174:177], v[58:61]
	v_mfma_f32_16x16x32_bf16 v[62:65], v[206:209], v[174:177], v[62:65]
	s_waitcnt lgkmcnt(0)
	v_mfma_f32_16x16x32_bf16 v[66:69], v[218:221], v[162:165], v[66:69]
	v_mfma_f32_16x16x32_bf16 v[70:73], v[222:225], v[162:165], v[70:73]
	v_mfma_f32_16x16x32_bf16 v[74:77], v[226:229], v[162:165], v[74:77]
	v_mfma_f32_16x16x32_bf16 v[78:81], v[230:233], v[162:165], v[78:81]
	v_mfma_f32_16x16x32_bf16 v[82:85], v[218:221], v[166:169], v[82:85]
	v_mfma_f32_16x16x32_bf16 v[86:89], v[222:225], v[166:169], v[86:89]
	v_mfma_f32_16x16x32_bf16 v[90:93], v[226:229], v[166:169], v[90:93]
	v_mfma_f32_16x16x32_bf16 v[94:97], v[230:233], v[166:169], v[94:97]
	v_mfma_f32_16x16x32_bf16 v[98:101], v[218:221], v[170:173], v[98:101]
	v_mfma_f32_16x16x32_bf16 v[102:105], v[222:225], v[170:173], v[102:105]
	v_mfma_f32_16x16x32_bf16 v[106:109], v[226:229], v[170:173], v[106:109]
	v_mfma_f32_16x16x32_bf16 v[110:113], v[230:233], v[170:173], v[110:113]
	v_mfma_f32_16x16x32_bf16 v[114:117], v[218:221], v[174:177], v[114:117]
	v_mfma_f32_16x16x32_bf16 v[118:121], v[222:225], v[174:177], v[118:121]
	v_mfma_f32_16x16x32_bf16 v[122:125], v[226:229], v[174:177], v[122:125]
	v_mfma_f32_16x16x32_bf16 v[126:129], v[230:233], v[174:177], v[126:129]
	s_waitcnt vmcnt(4)
	s_barrier
	v_add_u32_e32 v139, 0x10000, v134
	v_add_u32_e32 v140, 0x10000, v135
	ds_read_b128 v[162:165], v139 offset:0
	ds_read_b128 v[166:169], v139 offset:1024
	ds_read_b128 v[170:173], v139 offset:2048
	ds_read_b128 v[174:177], v139 offset:3072
	ds_read_b128 v[194:197], v140 offset:0
	ds_read_b128 v[198:201], v140 offset:1024
	ds_read_b128 v[202:205], v140 offset:2048
	ds_read_b128 v[206:209], v140 offset:3072
	ds_read_b128 v[218:221], v140 offset:8192
	ds_read_b128 v[222:225], v140 offset:9216
	ds_read_b128 v[226:229], v140 offset:10240
	ds_read_b128 v[230:233], v140 offset:11264
	s_waitcnt lgkmcnt(4)
	v_mfma_f32_16x16x32_bf16 v[2:5], v[194:197], v[162:165], v[2:5]
	v_mfma_f32_16x16x32_bf16 v[6:9], v[198:201], v[162:165], v[6:9]
	v_mfma_f32_16x16x32_bf16 v[10:13], v[202:205], v[162:165], v[10:13]
	v_mfma_f32_16x16x32_bf16 v[14:17], v[206:209], v[162:165], v[14:17]
	v_mfma_f32_16x16x32_bf16 v[18:21], v[194:197], v[166:169], v[18:21]
	v_mfma_f32_16x16x32_bf16 v[22:25], v[198:201], v[166:169], v[22:25]
	v_mfma_f32_16x16x32_bf16 v[26:29], v[202:205], v[166:169], v[26:29]
	v_mfma_f32_16x16x32_bf16 v[30:33], v[206:209], v[166:169], v[30:33]
	v_mfma_f32_16x16x32_bf16 v[34:37], v[194:197], v[170:173], v[34:37]
	v_mfma_f32_16x16x32_bf16 v[38:41], v[198:201], v[170:173], v[38:41]
	v_mfma_f32_16x16x32_bf16 v[42:45], v[202:205], v[170:173], v[42:45]
	v_mfma_f32_16x16x32_bf16 v[46:49], v[206:209], v[170:173], v[46:49]
	v_mfma_f32_16x16x32_bf16 v[50:53], v[194:197], v[174:177], v[50:53]
	v_mfma_f32_16x16x32_bf16 v[54:57], v[198:201], v[174:177], v[54:57]
	v_mfma_f32_16x16x32_bf16 v[58:61], v[202:205], v[174:177], v[58:61]
	v_mfma_f32_16x16x32_bf16 v[62:65], v[206:209], v[174:177], v[62:65]
	s_waitcnt lgkmcnt(0)
	v_mfma_f32_16x16x32_bf16 v[66:69], v[218:221], v[162:165], v[66:69]
	v_mfma_f32_16x16x32_bf16 v[70:73], v[222:225], v[162:165], v[70:73]
	v_mfma_f32_16x16x32_bf16 v[74:77], v[226:229], v[162:165], v[74:77]
	v_mfma_f32_16x16x32_bf16 v[78:81], v[230:233], v[162:165], v[78:81]
	v_mfma_f32_16x16x32_bf16 v[82:85], v[218:221], v[166:169], v[82:85]
	v_mfma_f32_16x16x32_bf16 v[86:89], v[222:225], v[166:169], v[86:89]
	v_mfma_f32_16x16x32_bf16 v[90:93], v[226:229], v[166:169], v[90:93]
	v_mfma_f32_16x16x32_bf16 v[94:97], v[230:233], v[166:169], v[94:97]
	v_mfma_f32_16x16x32_bf16 v[98:101], v[218:221], v[170:173], v[98:101]
	v_mfma_f32_16x16x32_bf16 v[102:105], v[222:225], v[170:173], v[102:105]
	v_mfma_f32_16x16x32_bf16 v[106:109], v[226:229], v[170:173], v[106:109]
	v_mfma_f32_16x16x32_bf16 v[110:113], v[230:233], v[170:173], v[110:113]
	v_mfma_f32_16x16x32_bf16 v[114:117], v[218:221], v[174:177], v[114:117]
	v_mfma_f32_16x16x32_bf16 v[118:121], v[222:225], v[174:177], v[118:121]
	v_mfma_f32_16x16x32_bf16 v[122:125], v[226:229], v[174:177], v[122:125]
	v_mfma_f32_16x16x32_bf16 v[126:129], v[230:233], v[174:177], v[126:129]
	s_waitcnt vmcnt(0)
	s_barrier
	v_add_u32_e32 v139, 0x18000, v134
	v_add_u32_e32 v140, 0x18000, v135
	ds_read_b128 v[162:165], v139 offset:0
	ds_read_b128 v[166:169], v139 offset:1024
	ds_read_b128 v[170:173], v139 offset:2048
	ds_read_b128 v[174:177], v139 offset:3072
	ds_read_b128 v[194:197], v140 offset:0
	ds_read_b128 v[198:201], v140 offset:1024
	ds_read_b128 v[202:205], v140 offset:2048
	ds_read_b128 v[206:209], v140 offset:3072
	ds_read_b128 v[218:221], v140 offset:8192
	ds_read_b128 v[222:225], v140 offset:9216
	ds_read_b128 v[226:229], v140 offset:10240
	ds_read_b128 v[230:233], v140 offset:11264
	s_waitcnt lgkmcnt(4)
	v_mfma_f32_16x16x32_bf16 v[2:5], v[194:197], v[162:165], v[2:5]
	v_mfma_f32_16x16x32_bf16 v[6:9], v[198:201], v[162:165], v[6:9]
	v_mfma_f32_16x16x32_bf16 v[10:13], v[202:205], v[162:165], v[10:13]
	v_mfma_f32_16x16x32_bf16 v[14:17], v[206:209], v[162:165], v[14:17]
	v_mfma_f32_16x16x32_bf16 v[18:21], v[194:197], v[166:169], v[18:21]
	v_mfma_f32_16x16x32_bf16 v[22:25], v[198:201], v[166:169], v[22:25]
	v_mfma_f32_16x16x32_bf16 v[26:29], v[202:205], v[166:169], v[26:29]
	v_mfma_f32_16x16x32_bf16 v[30:33], v[206:209], v[166:169], v[30:33]
	v_mfma_f32_16x16x32_bf16 v[34:37], v[194:197], v[170:173], v[34:37]
	v_mfma_f32_16x16x32_bf16 v[38:41], v[198:201], v[170:173], v[38:41]
	v_mfma_f32_16x16x32_bf16 v[42:45], v[202:205], v[170:173], v[42:45]
	v_mfma_f32_16x16x32_bf16 v[46:49], v[206:209], v[170:173], v[46:49]
	v_mfma_f32_16x16x32_bf16 v[50:53], v[194:197], v[174:177], v[50:53]
	v_mfma_f32_16x16x32_bf16 v[54:57], v[198:201], v[174:177], v[54:57]
	v_mfma_f32_16x16x32_bf16 v[58:61], v[202:205], v[174:177], v[58:61]
	v_mfma_f32_16x16x32_bf16 v[62:65], v[206:209], v[174:177], v[62:65]
	s_waitcnt lgkmcnt(0)
	v_mfma_f32_16x16x32_bf16 v[66:69], v[218:221], v[162:165], v[66:69]
	v_mfma_f32_16x16x32_bf16 v[70:73], v[222:225], v[162:165], v[70:73]
	v_mfma_f32_16x16x32_bf16 v[74:77], v[226:229], v[162:165], v[74:77]
	v_mfma_f32_16x16x32_bf16 v[78:81], v[230:233], v[162:165], v[78:81]
	v_mfma_f32_16x16x32_bf16 v[82:85], v[218:221], v[166:169], v[82:85]
	v_mfma_f32_16x16x32_bf16 v[86:89], v[222:225], v[166:169], v[86:89]
	v_mfma_f32_16x16x32_bf16 v[90:93], v[226:229], v[166:169], v[90:93]
	v_mfma_f32_16x16x32_bf16 v[94:97], v[230:233], v[166:169], v[94:97]
	v_mfma_f32_16x16x32_bf16 v[98:101], v[218:221], v[170:173], v[98:101]
	v_mfma_f32_16x16x32_bf16 v[102:105], v[222:225], v[170:173], v[102:105]
	v_mfma_f32_16x16x32_bf16 v[106:109], v[226:229], v[170:173], v[106:109]
	v_mfma_f32_16x16x32_bf16 v[110:113], v[230:233], v[170:173], v[110:113]
	v_mfma_f32_16x16x32_bf16 v[114:117], v[218:221], v[174:177], v[114:117]
	v_mfma_f32_16x16x32_bf16 v[118:121], v[222:225], v[174:177], v[118:121]
	v_mfma_f32_16x16x32_bf16 v[122:125], v[226:229], v[174:177], v[122:125]
	v_mfma_f32_16x16x32_bf16 v[126:129], v[230:233], v[174:177], v[126:129]
	s_branch .Lg2_a_kdone3
.Lg2_a_grpB2:
	v_mov_b32_e32 v178, 0
	v_mov_b32_e32 v179, 0
	v_mov_b32_e32 v180, 0
	v_mov_b32_e32 v181, 0
	v_mov_b32_e32 v182, 0
	v_mov_b32_e32 v183, 0
	v_mov_b32_e32 v184, 0
	v_mov_b32_e32 v185, 0
	v_mov_b32_e32 v186, 0
	v_mov_b32_e32 v187, 0
	v_mov_b32_e32 v188, 0
	v_mov_b32_e32 v189, 0
	v_mov_b32_e32 v190, 0
	v_mov_b32_e32 v191, 0
	v_mov_b32_e32 v192, 0
	v_mov_b32_e32 v193, 0
	v_mov_b32_e32 v218, 0
	v_mov_b32_e32 v219, 0
	v_mov_b32_e32 v220, 0
	v_mov_b32_e32 v221, 0
	v_mov_b32_e32 v222, 0
	v_mov_b32_e32 v223, 0
	v_mov_b32_e32 v224, 0
	v_mov_b32_e32 v225, 0
	v_mov_b32_e32 v226, 0
	v_mov_b32_e32 v227, 0
	v_mov_b32_e32 v228, 0
	v_mov_b32_e32 v229, 0
	v_mov_b32_e32 v230, 0
	v_mov_b32_e32 v231, 0
	v_mov_b32_e32 v232, 0
	v_mov_b32_e32 v233, 0
	s_mov_b32 s7, 7
.Lg2_a_klB5:
	s_waitcnt vmcnt(8)
	s_barrier
	v_add_u32_e32 v139, 0x0, v134
	v_add_u32_e32 v140, 0x0, v135
	ds_read_b128 v[162:165], v139 offset:0
	ds_read_b128 v[166:169], v139 offset:1024
	ds_read_b128 v[170:173], v139 offset:2048
	ds_read_b128 v[174:177], v139 offset:3072
	ds_read_b128 v[194:197], v140 offset:0
	ds_read_b128 v[198:201], v140 offset:1024
	ds_read_b128 v[202:205], v140 offset:2048
	ds_read_b128 v[206:209], v140 offset:3072
	v_mfma_f32_16x16x32_bf16 v[66:69], v[218:221], v[178:181], v[66:69]
	v_mfma_f32_16x16x32_bf16 v[70:73], v[222:225], v[178:181], v[70:73]
	v_mfma_f32_16x16x32_bf16 v[74:77], v[226:229], v[178:181], v[74:77]
	s_add_u32 m0, s6, 0x18000
	s_nop 0
	global_load_lds_dwordx4 v136, s[0:1]
	v_mfma_f32_16x16x32_bf16 v[78:81], v[230:233], v[178:181], v[78:81]
	v_mfma_f32_16x16x32_bf16 v[82:85], v[218:221], v[182:185], v[82:85]
	v_mfma_f32_16x16x32_bf16 v[86:89], v[222:225], v[182:185], v[86:89]
	v_mfma_f32_16x16x32_bf16 v[90:93], v[226:229], v[182:185], v[90:93]
	s_add_u32 m0, s6, 0x1a000
	s_nop 0
	global_load_lds_dwordx4 v137, s[0:1]
	v_mfma_f32_16x16x32_bf16 v[94:97], v[230:233], v[182:185], v[94:97]
	v_mfma_f32_16x16x32_bf16 v[98:101], v[218:221], v[186:189], v[98:101]
	v_mfma_f32_16x16x32_bf16 v[102:105], v[222:225], v[186:189], v[102:105]
	v_mfma_f32_16x16x32_bf16 v[106:109], v[226:229], v[186:189], v[106:109]
	s_add_u32 m0, s6, 0x1c000
	s_nop 0
	global_load_lds_dwordx4 v136, s[2:3]
	v_mfma_f32_16x16x32_bf16 v[110:113], v[230:233], v[186:189], v[110:113]
	v_mfma_f32_16x16x32_bf16 v[114:117], v[218:221], v[190:193], v[114:117]
	v_mfma_f32_16x16x32_bf16 v[118:121], v[222:225], v[190:193], v[118:121]
	v_mfma_f32_16x16x32_bf16 v[122:125], v[226:229], v[190:193], v[122:125]
	s_add_u32 m0, s6, 0x1e000
	s_nop 0
	global_load_lds_dwordx4 v137, s[2:3]
	v_mfma_f32_16x16x32_bf16 v[126:129], v[230:233], v[190:193], v[126:129]
	s_add_u32 s0, s0, 64
	s_addc_u32 s1, s1, 0
	s_add_u32 s2, s2, 64
	s_addc_u32 s3, s3, 0
	ds_read_b128 v[218:221], v140 offset:8192
	ds_read_b128 v[222:225], v140 offset:9216
	ds_read_b128 v[226:229], v140 offset:10240
	ds_read_b128 v[230:233], v140 offset:11264
	s_waitcnt lgkmcnt(4)
	v_mfma_f32_16x16x32_bf16 v[2:5], v[194:197], v[162:165], v[2:5]
	v_mfma_f32_16x16x32_bf16 v[6:9], v[198:201], v[162:165], v[6:9]
	v_mfma_f32_16x16x32_bf16 v[10:13], v[202:205], v[162:165], v[10:13]
	v_mfma_f32_16x16x32_bf16 v[14:17], v[206:209], v[162:165], v[14:17]
	v_mfma_f32_16x16x32_bf16 v[18:21], v[194:197], v[166:169], v[18:21]
	v_mfma_f32_16x16x32_bf16 v[22:25], v[198:201], v[166:169], v[22:25]
	v_mfma_f32_16x16x32_bf16 v[26:29], v[202:205], v[166:169], v[26:29]
	v_mfma_f32_16x16x32_bf16 v[30:33], v[206:209], v[166:169], v[30:33]
	v_mfma_f32_16x16x32_bf16 v[34:37], v[194:197], v[170:173], v[34:37]
	v_mfma_f32_16x16x32_bf16 v[38:41], v[198:201], v[170:173], v[38:41]
	v_mfma_f32_16x16x32_bf16 v[42:45], v[202:205], v[170:173], v[42:45]
	v_mfma_f32_16x16x32_bf16 v[46:49], v[206:209], v[170:173], v[46:49]
	v_mfma_f32_16x16x32_bf16 v[50:53], v[194:197], v[174:177], v[50:53]
	v_mfma_f32_16x16x32_bf16 v[54:57], v[198:201], v[174:177], v[54:57]
	v_mfma_f32_16x16x32_bf16 v[58:61], v[202:205], v[174:177], v[58:61]
	v_mfma_f32_16x16x32_bf16 v[62:65], v[206:209], v[174:177], v[62:65]
	s_waitcnt lgkmcnt(0)
	s_waitcnt vmcnt(8)
	s_barrier
	v_add_u32_e32 v139, 0x8000, v134
	v_add_u32_e32 v140, 0x8000, v135
	ds_read_b128 v[178:181], v139 offset:0
	ds_read_b128 v[182:185], v139 offset:1024
	ds_read_b128 v[186:189], v139 offset:2048
	ds_read_b128 v[190:193], v139 offset:3072
	ds_read_b128 v[194:197], v140 offset:0
	ds_read_b128 v[198:201], v140 offset:1024
	ds_read_b128 v[202:205], v140 offset:2048
	ds_read_b128 v[206:209], v140 offset:3072
	v_mfma_f32_16x16x32_bf16 v[66:69], v[218:221], v[162:165], v[66:69]
	v_mfma_f32_16x16x32_bf16 v[70:73], v[222:225], v[162:165], v[70:73]
	v_mfma_f32_16x16x32_bf16 v[74:77], v[226:229], v[162:165], v[74:77]
	s_add_u32 m0, s6, 0x0
	s_nop 0
	global_load_lds_dwordx4 v136, s[0:1]
	v_mfma_f32_16x16x32_bf16 v[78:81], v[230:233], v[162:165], v[78:81]
	v_mfma_f32_16x16x32_bf16 v[82:85], v[218:221], v[166:169], v[82:85]
	v_mfma_f32_16x16x32_bf16 v[86:89], v[222:225], v[166:169], v[86:89]
	v_mfma_f32_16x16x32_bf16 v[90:93], v[226:229], v[166:169], v[90:93]
	s_add_u32 m0, s6, 0x2000
	s_nop 0
	global_load_lds_dwordx4 v137, s[0:1]
	v_mfma_f32_16x16x32_bf16 v[94:97], v[230:233], v[166:169], v[94:97]
	v_mfma_f32_16x16x32_bf16 v[98:101], v[218:221], v[170:173], v[98:101]
	v_mfma_f32_16x16x32_bf16 v[102:105], v[222:225], v[170:173], v[102:105]
	v_mfma_f32_16x16x32_bf16 v[106:109], v[226:229], v[170:173], v[106:109]
	s_add_u32 m0, s6, 0x4000
	s_nop 0
	global_load_lds_dwordx4 v136, s[2:3]
	v_mfma_f32_16x16x32_bf16 v[110:113], v[230:233], v[170:173], v[110:113]
	v_mfma_f32_16x16x32_bf16 v[114:117], v[218:221], v[174:177], v[114:117]
	v_mfma_f32_16x16x32_bf16 v[118:121], v[222:225], v[174:177], v[118:121]
	v_mfma_f32_16x16x32_bf16 v[122:125], v[226:229], v[174:177], v[122:125]
	s_add_u32 m0, s6, 0x6000
	s_nop 0
	global_load_lds_dwordx4 v137, s[2:3]
	v_mfma_f32_16x16x32_bf16 v[126:129], v[230:233], v[174:177], v[126:129]
	s_add_u32 s0, s0, 64
	s_addc_u32 s1, s1, 0
	s_add_u32 s2, s2, 64
	s_addc_u32 s3, s3, 0
	ds_read_b128 v[218:221], v140 offset:8192
	ds_read_b128 v[222:225], v140 offset:9216
	ds_read_b128 v[226:229], v140 offset:10240
	ds_read_b128 v[230:233], v140 offset:11264
	s_waitcnt lgkmcnt(4)
	v_mfma_f32_16x16x32_bf16 v[2:5], v[194:197], v[178:181], v[2:5]
	v_mfma_f32_16x16x32_bf16 v[6:9], v[198:201], v[178:181], v[6:9]
	v_mfma_f32_16x16x32_bf16 v[10:13], v[202:205], v[178:181], v[10:13]
	v_mfma_f32_16x16x32_bf16 v[14:17], v[206:209], v[178:181], v[14:17]
	v_mfma_f32_16x16x32_bf16 v[18:21], v[194:197], v[182:185], v[18:21]
	v_mfma_f32_16x16x32_bf16 v[22:25], v[198:201], v[182:185], v[22:25]
	v_mfma_f32_16x16x32_bf16 v[26:29], v[202:205], v[182:185], v[26:29]
	v_mfma_f32_16x16x32_bf16 v[30:33], v[206:209], v[182:185], v[30:33]
	v_mfma_f32_16x16x32_bf16 v[34:37], v[194:197], v[186:189], v[34:37]
	v_mfma_f32_16x16x32_bf16 v[38:41], v[198:201], v[186:189], v[38:41]
	v_mfma_f32_16x16x32_bf16 v[42:45], v[202:205], v[186:189], v[42:45]
	v_mfma_f32_16x16x32_bf16 v[46:49], v[206:209], v[186:189], v[46:49]
	v_mfma_f32_16x16x32_bf16 v[50:53], v[194:197], v[190:193], v[50:53]
	v_mfma_f32_16x16x32_bf16 v[54:57], v[198:201], v[190:193], v[54:57]
	v_mfma_f32_16x16x32_bf16 v[58:61], v[202:205], v[190:193], v[58:61]
	v_mfma_f32_16x16x32_bf16 v[62:65], v[206:209], v[190:193], v[62:65]
	s_waitcnt lgkmcnt(0)
	s_waitcnt vmcnt(8)
	s_barrier
	v_add_u32_e32 v139, 0x10000, v134
	v_add_u32_e32 v140, 0x10000, v135
	ds_read_b128 v[162:165], v139 offset:0
	ds_read_b128 v[166:169], v139 offset:1024
	ds_read_b128 v[170:173], v139 offset:2048
	ds_read_b128 v[174:177], v139 offset:3072
	ds_read_b128 v[194:197], v140 offset:0
	ds_read_b128 v[198:201], v140 offset:1024
	ds_read_b128 v[202:205], v140 offset:2048
	ds_read_b128 v[206:209], v140 offset:3072
	v_mfma_f32_16x16x32_bf16 v[66:69], v[218:221], v[178:181], v[66:69]
	v_mfma_f32_16x16x32_bf16 v[70:73], v[222:225], v[178:181], v[70:73]
	v_mfma_f32_16x16x32_bf16 v[74:77], v[226:229], v[178:181], v[74:77]
	s_add_u32 m0, s6, 0x8000
	s_nop 0
	global_load_lds_dwordx4 v136, s[0:1]
	v_mfma_f32_16x16x32_bf16 v[78:81], v[230:233], v[178:181], v[78:81]
	v_mfma_f32_16x16x32_bf16 v[82:85], v[218:221], v[182:185], v[82:85]
	v_mfma_f32_16x16x32_bf16 v[86:89], v[222:225], v[182:185], v[86:89]
	v_mfma_f32_16x16x32_bf16 v[90:93], v[226:229], v[182:185], v[90:93]
	s_add_u32 m0, s6, 0xa000
	s_nop 0
	global_load_lds_dwordx4 v137, s[0:1]
	v_mfma_f32_16x16x32_bf16 v[94:97], v[230:233], v[182:185], v[94:97]
	v_mfma_f32_16x16x32_bf16 v[98:101], v[218:221], v[186:189], v[98:101]
	v_mfma_f32_16x16x32_bf16 v[102:105], v[222:225], v[186:189], v[102:105]
	v_mfma_f32_16x16x32_bf16 v[106:109], v[226:229], v[186:189], v[106:109]
	s_add_u32 m0, s6, 0xc000
	s_nop 0
	global_load_lds_dwordx4 v136, s[2:3]
	v_mfma_f32_16x16x32_bf16 v[110:113], v[230:233], v[186:189], v[110:113]
	v_mfma_f32_16x16x32_bf16 v[114:117], v[218:221], v[190:193], v[114:117]
	v_mfma_f32_16x16x32_bf16 v[118:121], v[222:225], v[190:193], v[118:121]
	v_mfma_f32_16x16x32_bf16 v[122:125], v[226:229], v[190:193], v[122:125]
	s_add_u32 m0, s6, 0xe000
	s_nop 0
	global_load_lds_dwordx4 v137, s[2:3]
	v_mfma_f32_16x16x32_bf16 v[126:129], v[230:233], v[190:193], v[126:129]
	s_add_u32 s0, s0, 64
	s_addc_u32 s1, s1, 0
	s_add_u32 s2, s2, 64
	s_addc_u32 s3, s3, 0
	ds_read_b128 v[218:221], v140 offset:8192
	ds_read_b128 v[222:225], v140 offset:9216
	ds_read_b128 v[226:229], v140 offset:10240
	ds_read_b128 v[230:233], v140 offset:11264
	s_waitcnt lgkmcnt(4)
	v_mfma_f32_16x16x32_bf16 v[2:5], v[194:197], v[162:165], v[2:5]
	v_mfma_f32_16x16x32_bf16 v[6:9], v[198:201], v[162:165], v[6:9]
	v_mfma_f32_16x16x32_bf16 v[10:13], v[202:205], v[162:165], v[10:13]
	v_mfma_f32_16x16x32_bf16 v[14:17], v[206:209], v[162:165], v[14:17]
	v_mfma_f32_16x16x32_bf16 v[18:21], v[194:197], v[166:169], v[18:21]
	v_mfma_f32_16x16x32_bf16 v[22:25], v[198:201], v[166:169], v[22:25]
	v_mfma_f32_16x16x32_bf16 v[26:29], v[202:205], v[166:169], v[26:29]
	v_mfma_f32_16x16x32_bf16 v[30:33], v[206:209], v[166:169], v[30:33]
	v_mfma_f32_16x16x32_bf16 v[34:37], v[194:197], v[170:173], v[34:37]
	v_mfma_f32_16x16x32_bf16 v[38:41], v[198:201], v[170:173], v[38:41]
	v_mfma_f32_16x16x32_bf16 v[42:45], v[202:205], v[170:173], v[42:45]
	v_mfma_f32_16x16x32_bf16 v[46:49], v[206:209], v[170:173], v[46:49]
	v_mfma_f32_16x16x32_bf16 v[50:53], v[194:197], v[174:177], v[50:53]
	v_mfma_f32_16x16x32_bf16 v[54:57], v[198:201], v[174:177], v[54:57]
	v_mfma_f32_16x16x32_bf16 v[58:61], v[202:205], v[174:177], v[58:61]
	v_mfma_f32_16x16x32_bf16 v[62:65], v[206:209], v[174:177], v[62:65]
	s_waitcnt lgkmcnt(0)
	s_waitcnt vmcnt(8)
	s_barrier
	v_add_u32_e32 v139, 0x18000, v134
	v_add_u32_e32 v140, 0x18000, v135
	ds_read_b128 v[178:181], v139 offset:0
	ds_read_b128 v[182:185], v139 offset:1024
	ds_read_b128 v[186:189], v139 offset:2048
	ds_read_b128 v[190:193], v139 offset:3072
	ds_read_b128 v[194:197], v140 offset:0
	ds_read_b128 v[198:201], v140 offset:1024
	ds_read_b128 v[202:205], v140 offset:2048
	ds_read_b128 v[206:209], v140 offset:3072
	v_mfma_f32_16x16x32_bf16 v[66:69], v[218:221], v[162:165], v[66:69]
	v_mfma_f32_16x16x32_bf16 v[70:73], v[222:225], v[162:165], v[70:73]
	v_mfma_f32_16x16x32_bf16 v[74:77], v[226:229], v[162:165], v[74:77]
	s_add_u32 m0, s6, 0x10000
	s_nop 0
	global_load_lds_dwordx4 v136, s[0:1]
	v_mfma_f32_16x16x32_bf16 v[78:81], v[230:233], v[162:165], v[78:81]
	v_mfma_f32_16x16x32_bf16 v[82:85], v[218:221], v[166:169], v[82:85]
	v_mfma_f32_16x16x32_bf16 v[86:89], v[222:225], v[166:169], v[86:89]
	v_mfma_f32_16x16x32_bf16 v[90:93], v[226:229], v[166:169], v[90:93]
	s_add_u32 m0, s6, 0x12000
	s_nop 0
	global_load_lds_dwordx4 v137, s[0:1]
	v_mfma_f32_16x16x32_bf16 v[94:97], v[230:233], v[166:169], v[94:97]
	v_mfma_f32_16x16x32_bf16 v[98:101], v[218:221], v[170:173], v[98:101]
	v_mfma_f32_16x16x32_bf16 v[102:105], v[222:225], v[170:173], v[102:105]
	v_mfma_f32_16x16x32_bf16 v[106:109], v[226:229], v[170:173], v[106:109]
	s_add_u32 m0, s6, 0x14000
	s_nop 0
	global_load_lds_dwordx4 v136, s[2:3]
	v_mfma_f32_16x16x32_bf16 v[110:113], v[230:233], v[170:173], v[110:113]
	v_mfma_f32_16x16x32_bf16 v[114:117], v[218:221], v[174:177], v[114:117]
	v_mfma_f32_16x16x32_bf16 v[118:121], v[222:225], v[174:177], v[118:121]
	v_mfma_f32_16x16x32_bf16 v[122:125], v[226:229], v[174:177], v[122:125]
	s_add_u32 m0, s6, 0x16000
	s_nop 0
	global_load_lds_dwordx4 v137, s[2:3]
	v_mfma_f32_16x16x32_bf16 v[126:129], v[230:233], v[174:177], v[126:129]
	s_add_u32 s0, s0, 64
	s_addc_u32 s1, s1, 0
	s_add_u32 s2, s2, 64
	s_addc_u32 s3, s3, 0
	ds_read_b128 v[218:221], v140 offset:8192
	ds_read_b128 v[222:225], v140 offset:9216
	ds_read_b128 v[226:229], v140 offset:10240
	ds_read_b128 v[230:233], v140 offset:11264
	s_waitcnt lgkmcnt(4)
	v_mfma_f32_16x16x32_bf16 v[2:5], v[194:197], v[178:181], v[2:5]
	v_mfma_f32_16x16x32_bf16 v[6:9], v[198:201], v[178:181], v[6:9]
	v_mfma_f32_16x16x32_bf16 v[10:13], v[202:205], v[178:181], v[10:13]
	v_mfma_f32_16x16x32_bf16 v[14:17], v[206:209], v[178:181], v[14:17]
	v_mfma_f32_16x16x32_bf16 v[18:21], v[194:197], v[182:185], v[18:21]
	v_mfma_f32_16x16x32_bf16 v[22:25], v[198:201], v[182:185], v[22:25]
	v_mfma_f32_16x16x32_bf16 v[26:29], v[202:205], v[182:185], v[26:29]
	v_mfma_f32_16x16x32_bf16 v[30:33], v[206:209], v[182:185], v[30:33]
	v_mfma_f32_16x16x32_bf16 v[34:37], v[194:197], v[186:189], v[34:37]
	v_mfma_f32_16x16x32_bf16 v[38:41], v[198:201], v[186:189], v[38:41]
	v_mfma_f32_16x16x32_bf16 v[42:45], v[202:205], v[186:189], v[42:45]
	v_mfma_f32_16x16x32_bf16 v[46:49], v[206:209], v[186:189], v[46:49]
	v_mfma_f32_16x16x32_bf16 v[50:53], v[194:197], v[190:193], v[50:53]
	v_mfma_f32_16x16x32_bf16 v[54:57], v[198:201], v[190:193], v[54:57]
	v_mfma_f32_16x16x32_bf16 v[58:61], v[202:205], v[190:193], v[58:61]
	v_mfma_f32_16x16x32_bf16 v[62:65], v[206:209], v[190:193], v[62:65]
	s_waitcnt lgkmcnt(0)
	s_sub_u32 s7, s7, 1
	s_cmp_lg_u32 s7, 0
	s_cbranch_scc1 .Lg2_a_klB5
	s_waitcnt vmcnt(8)
	s_barrier
	v_add_u32_e32 v139, 0x0, v134
	v_add_u32_e32 v140, 0x0, v135
	ds_read_b128 v[162:165], v139 offset:0
	ds_read_b128 v[166:169], v139 offset:1024
	ds_read_b128 v[170:173], v139 offset:2048
	ds_read_b128 v[174:177], v139 offset:3072
	ds_read_b128 v[194:197], v140 offset:0
	ds_read_b128 v[198:201], v140 offset:1024
	ds_read_b128 v[202:205], v140 offset:2048
	ds_read_b128 v[206:209], v140 offset:3072
	v_mfma_f32_16x16x32_bf16 v[66:69], v[218:221], v[178:181], v[66:69]
	v_mfma_f32_16x16x32_bf16 v[70:73], v[222:225], v[178:181], v[70:73]
	v_mfma_f32_16x16x32_bf16 v[74:77], v[226:229], v[178:181], v[74:77]
	s_add_u32 m0, s6, 0x18000
	s_nop 0
	global_load_lds_dwordx4 v136, s[0:1]
	v_mfma_f32_16x16x32_bf16 v[78:81], v[230:233], v[178:181], v[78:81]
	v_mfma_f32_16x16x32_bf16 v[82:85], v[218:221], v[182:185], v[82:85]
	v_mfma_f32_16x16x32_bf16 v[86:89], v[222:225], v[182:185], v[86:89]
	v_mfma_f32_16x16x32_bf16 v[90:93], v[226:229], v[182:185], v[90:93]
	s_add_u32 m0, s6, 0x1a000
	s_nop 0
	global_load_lds_dwordx4 v137, s[0:1]
	v_mfma_f32_16x16x32_bf16 v[94:97], v[230:233], v[182:185], v[94:97]
	v_mfma_f32_16x16x32_bf16 v[98:101], v[218:221], v[186:189], v[98:101]
	v_mfma_f32_16x16x32_bf16 v[102:105], v[222:225], v[186:189], v[102:105]
	v_mfma_f32_16x16x32_bf16 v[106:109], v[226:229], v[186:189], v[106:109]
	s_add_u32 m0, s6, 0x1c000
	s_nop 0
	global_load_lds_dwordx4 v136, s[2:3]
	v_mfma_f32_16x16x32_bf16 v[110:113], v[230:233], v[186:189], v[110:113]
	v_mfma_f32_16x16x32_bf16 v[114:117], v[218:221], v[190:193], v[114:117]
	v_mfma_f32_16x16x32_bf16 v[118:121], v[222:225], v[190:193], v[118:121]
	v_mfma_f32_16x16x32_bf16 v[122:125], v[226:229], v[190:193], v[122:125]
	s_add_u32 m0, s6, 0x1e000
	s_nop 0
	global_load_lds_dwordx4 v137, s[2:3]
	v_mfma_f32_16x16x32_bf16 v[126:129], v[230:233], v[190:193], v[126:129]
	s_add_u32 s0, s0, 64
	s_addc_u32 s1, s1, 0
	s_add_u32 s2, s2, 64
	s_addc_u32 s3, s3, 0
	ds_read_b128 v[218:221], v140 offset:8192
	ds_read_b128 v[222:225], v140 offset:9216
	ds_read_b128 v[226:229], v140 offset:10240
	ds_read_b128 v[230:233], v140 offset:11264
	s_waitcnt lgkmcnt(4)
	v_mfma_f32_16x16x32_bf16 v[2:5], v[194:197], v[162:165], v[2:5]
	v_mfma_f32_16x16x32_bf16 v[6:9], v[198:201], v[162:165], v[6:9]
	v_mfma_f32_16x16x32_bf16 v[10:13], v[202:205], v[162:165], v[10:13]
	v_mfma_f32_16x16x32_bf16 v[14:17], v[206:209], v[162:165], v[14:17]
	v_mfma_f32_16x16x32_bf16 v[18:21], v[194:197], v[166:169], v[18:21]
	v_mfma_f32_16x16x32_bf16 v[22:25], v[198:201], v[166:169], v[22:25]
	v_mfma_f32_16x16x32_bf16 v[26:29], v[202:205], v[166:169], v[26:29]
	v_mfma_f32_16x16x32_bf16 v[30:33], v[206:209], v[166:169], v[30:33]
	v_mfma_f32_16x16x32_bf16 v[34:37], v[194:197], v[170:173], v[34:37]
	v_mfma_f32_16x16x32_bf16 v[38:41], v[198:201], v[170:173], v[38:41]
	v_mfma_f32_16x16x32_bf16 v[42:45], v[202:205], v[170:173], v[42:45]
	v_mfma_f32_16x16x32_bf16 v[46:49], v[206:209], v[170:173], v[46:49]
	v_mfma_f32_16x16x32_bf16 v[50:53], v[194:197], v[174:177], v[50:53]
	v_mfma_f32_16x16x32_bf16 v[54:57], v[198:201], v[174:177], v[54:57]
	v_mfma_f32_16x16x32_bf16 v[58:61], v[202:205], v[174:177], v[58:61]
	v_mfma_f32_16x16x32_bf16 v[62:65], v[206:209], v[174:177], v[62:65]
	s_waitcnt lgkmcnt(0)
	s_waitcnt vmcnt(8)
	s_barrier
	v_add_u32_e32 v139, 0x8000, v134
	v_add_u32_e32 v140, 0x8000, v135
	ds_read_b128 v[178:181], v139 offset:0
	ds_read_b128 v[182:185], v139 offset:1024
	ds_read_b128 v[186:189], v139 offset:2048
	ds_read_b128 v[190:193], v139 offset:3072
	ds_read_b128 v[194:197], v140 offset:0
	ds_read_b128 v[198:201], v140 offset:1024
	ds_read_b128 v[202:205], v140 offset:2048
	ds_read_b128 v[206:209], v140 offset:3072
	v_mfma_f32_16x16x32_bf16 v[66:69], v[218:221], v[162:165], v[66:69]
	v_mfma_f32_16x16x32_bf16 v[70:73], v[222:225], v[162:165], v[70:73]
	v_mfma_f32_16x16x32_bf16 v[74:77], v[226:229], v[162:165], v[74:77]
	v_mfma_f32_16x16x32_bf16 v[78:81], v[230:233], v[162:165], v[78:81]
	v_mfma_f32_16x16x32_bf16 v[82:85], v[218:221], v[166:169], v[82:85]
	v_mfma_f32_16x16x32_bf16 v[86:89], v[222:225], v[166:169], v[86:89]
	v_mfma_f32_16x16x32_bf16 v[90:93], v[226:229], v[166:169], v[90:93]
	v_mfma_f32_16x16x32_bf16 v[94:97], v[230:233], v[166:169], v[94:97]
	v_mfma_f32_16x16x32_bf16 v[98:101], v[218:221], v[170:173], v[98:101]
	v_mfma_f32_16x16x32_bf16 v[102:105], v[222:225], v[170:173], v[102:105]
	v_mfma_f32_16x16x32_bf16 v[106:109], v[226:229], v[170:173], v[106:109]
	v_mfma_f32_16x16x32_bf16 v[110:113], v[230:233], v[170:173], v[110:113]
	v_mfma_f32_16x16x32_bf16 v[114:117], v[218:221], v[174:177], v[114:117]
	v_mfma_f32_16x16x32_bf16 v[118:121], v[222:225], v[174:177], v[118:121]
	v_mfma_f32_16x16x32_bf16 v[122:125], v[226:229], v[174:177], v[122:125]
	v_mfma_f32_16x16x32_bf16 v[126:129], v[230:233], v[174:177], v[126:129]
	ds_read_b128 v[218:221], v140 offset:8192
	ds_read_b128 v[222:225], v140 offset:9216
	ds_read_b128 v[226:229], v140 offset:10240
	ds_read_b128 v[230:233], v140 offset:11264
	s_waitcnt lgkmcnt(4)
	v_mfma_f32_16x16x32_bf16 v[2:5], v[194:197], v[178:181], v[2:5]
	v_mfma_f32_16x16x32_bf16 v[6:9], v[198:201], v[178:181], v[6:9]
	v_mfma_f32_16x16x32_bf16 v[10:13], v[202:205], v[178:181], v[10:13]
	v_mfma_f32_16x16x32_bf16 v[14:17], v[206:209], v[178:181], v[14:17]
	v_mfma_f32_16x16x32_bf16 v[18:21], v[194:197], v[182:185], v[18:21]
	v_mfma_f32_16x16x32_bf16 v[22:25], v[198:201], v[182:185], v[22:25]
	v_mfma_f32_16x16x32_bf16 v[26:29], v[202:205], v[182:185], v[26:29]
	v_mfma_f32_16x16x32_bf16 v[30:33], v[206:209], v[182:185], v[30:33]
	v_mfma_f32_16x16x32_bf16 v[34:37], v[194:197], v[186:189], v[34:37]
	v_mfma_f32_16x16x32_bf16 v[38:41], v[198:201], v[186:189], v[38:41]
	v_mfma_f32_16x16x32_bf16 v[42:45], v[202:205], v[186:189], v[42:45]
	v_mfma_f32_16x16x32_bf16 v[46:49], v[206:209], v[186:189], v[46:49]
	v_mfma_f32_16x16x32_bf16 v[50:53], v[194:197], v[190:193], v[50:53]
	v_mfma_f32_16x16x32_bf16 v[54:57], v[198:201], v[190:193], v[54:57]
	v_mfma_f32_16x16x32_bf16 v[58:61], v[202:205], v[190:193], v[58:61]
	v_mfma_f32_16x16x32_bf16 v[62:65], v[206:209], v[190:193], v[62:65]
	s_waitcnt lgkmcnt(0)
	s_waitcnt vmcnt(4)
	s_barrier
	v_add_u32_e32 v139, 0x10000, v134
	v_add_u32_e32 v140, 0x10000, v135
	ds_read_b128 v[162:165], v139 offset:0
	ds_read_b128 v[166:169], v139 offset:1024
	ds_read_b128 v[170:173], v139 offset:2048
	ds_read_b128 v[174:177], v139 offset:3072
	ds_read_b128 v[194:197], v140 offset:0
	ds_read_b128 v[198:201], v140 offset:1024
	ds_read_b128 v[202:205], v140 offset:2048
	ds_read_b128 v[206:209], v140 offset:3072
	v_mfma_f32_16x16x32_bf16 v[66:69], v[218:221], v[178:181], v[66:69]
	v_mfma_f32_16x16x32_bf16 v[70:73], v[222:225], v[178:181], v[70:73]
	v_mfma_f32_16x16x32_bf16 v[74:77], v[226:229], v[178:181], v[74:77]
	v_mfma_f32_16x16x32_bf16 v[78:81], v[230:233], v[178:181], v[78:81]
	v_mfma_f32_16x16x32_bf16 v[82:85], v[218:221], v[182:185], v[82:85]
	v_mfma_f32_16x16x32_bf16 v[86:89], v[222:225], v[182:185], v[86:89]
	v_mfma_f32_16x16x32_bf16 v[90:93], v[226:229], v[182:185], v[90:93]
	v_mfma_f32_16x16x32_bf16 v[94:97], v[230:233], v[182:185], v[94:97]
	v_mfma_f32_16x16x32_bf16 v[98:101], v[218:221], v[186:189], v[98:101]
	v_mfma_f32_16x16x32_bf16 v[102:105], v[222:225], v[186:189], v[102:105]
	v_mfma_f32_16x16x32_bf16 v[106:109], v[226:229], v[186:189], v[106:109]
	v_mfma_f32_16x16x32_bf16 v[110:113], v[230:233], v[186:189], v[110:113]
	v_mfma_f32_16x16x32_bf16 v[114:117], v[218:221], v[190:193], v[114:117]
	v_mfma_f32_16x16x32_bf16 v[118:121], v[222:225], v[190:193], v[118:121]
	v_mfma_f32_16x16x32_bf16 v[122:125], v[226:229], v[190:193], v[122:125]
	v_mfma_f32_16x16x32_bf16 v[126:129], v[230:233], v[190:193], v[126:129]
	ds_read_b128 v[218:221], v140 offset:8192
	ds_read_b128 v[222:225], v140 offset:9216
	ds_read_b128 v[226:229], v140 offset:10240
	ds_read_b128 v[230:233], v140 offset:11264
	s_waitcnt lgkmcnt(4)
	v_mfma_f32_16x16x32_bf16 v[2:5], v[194:197], v[162:165], v[2:5]
	v_mfma_f32_16x16x32_bf16 v[6:9], v[198:201], v[162:165], v[6:9]
	v_mfma_f32_16x16x32_bf16 v[10:13], v[202:205], v[162:165], v[10:13]
	v_mfma_f32_16x16x32_bf16 v[14:17], v[206:209], v[162:165], v[14:17]
	v_mfma_f32_16x16x32_bf16 v[18:21], v[194:197], v[166:169], v[18:21]
	v_mfma_f32_16x16x32_bf16 v[22:25], v[198:201], v[166:169], v[22:25]
	v_mfma_f32_16x16x32_bf16 v[26:29], v[202:205], v[166:169], v[26:29]
	v_mfma_f32_16x16x32_bf16 v[30:33], v[206:209], v[166:169], v[30:33]
	v_mfma_f32_16x16x32_bf16 v[34:37], v[194:197], v[170:173], v[34:37]
	v_mfma_f32_16x16x32_bf16 v[38:41], v[198:201], v[170:173], v[38:41]
	v_mfma_f32_16x16x32_bf16 v[42:45], v[202:205], v[170:173], v[42:45]
	v_mfma_f32_16x16x32_bf16 v[46:49], v[206:209], v[170:173], v[46:49]
	v_mfma_f32_16x16x32_bf16 v[50:53], v[194:197], v[174:177], v[50:53]
	v_mfma_f32_16x16x32_bf16 v[54:57], v[198:201], v[174:177], v[54:57]
	v_mfma_f32_16x16x32_bf16 v[58:61], v[202:205], v[174:177], v[58:61]
	v_mfma_f32_16x16x32_bf16 v[62:65], v[206:209], v[174:177], v[62:65]
	s_waitcnt lgkmcnt(0)
	s_waitcnt vmcnt(0)
	s_barrier
	v_add_u32_e32 v139, 0x18000, v134
	v_add_u32_e32 v140, 0x18000, v135
	ds_read_b128 v[178:181], v139 offset:0
	ds_read_b128 v[182:185], v139 offset:1024
	ds_read_b128 v[186:189], v139 offset:2048
	ds_read_b128 v[190:193], v139 offset:3072
	ds_read_b128 v[194:197], v140 offset:0
	ds_read_b128 v[198:201], v140 offset:1024
	ds_read_b128 v[202:205], v140 offset:2048
	ds_read_b128 v[206:209], v140 offset:3072
	v_mfma_f32_16x16x32_bf16 v[66:69], v[218:221], v[162:165], v[66:69]
	v_mfma_f32_16x16x32_bf16 v[70:73], v[222:225], v[162:165], v[70:73]
	v_mfma_f32_16x16x32_bf16 v[74:77], v[226:229], v[162:165], v[74:77]
	v_mfma_f32_16x16x32_bf16 v[78:81], v[230:233], v[162:165], v[78:81]
	v_mfma_f32_16x16x32_bf16 v[82:85], v[218:221], v[166:169], v[82:85]
	v_mfma_f32_16x16x32_bf16 v[86:89], v[222:225], v[166:169], v[86:89]
	v_mfma_f32_16x16x32_bf16 v[90:93], v[226:229], v[166:169], v[90:93]
	v_mfma_f32_16x16x32_bf16 v[94:97], v[230:233], v[166:169], v[94:97]
	v_mfma_f32_16x16x32_bf16 v[98:101], v[218:221], v[170:173], v[98:101]
	v_mfma_f32_16x16x32_bf16 v[102:105], v[222:225], v[170:173], v[102:105]
	v_mfma_f32_16x16x32_bf16 v[106:109], v[226:229], v[170:173], v[106:109]
	v_mfma_f32_16x16x32_bf16 v[110:113], v[230:233], v[170:173], v[110:113]
	v_mfma_f32_16x16x32_bf16 v[114:117], v[218:221], v[174:177], v[114:117]
	v_mfma_f32_16x16x32_bf16 v[118:121], v[222:225], v[174:177], v[118:121]
	v_mfma_f32_16x16x32_bf16 v[122:125], v[226:229], v[174:177], v[122:125]
	v_mfma_f32_16x16x32_bf16 v[126:129], v[230:233], v[174:177], v[126:129]
	ds_read_b128 v[218:221], v140 offset:8192
	ds_read_b128 v[222:225], v140 offset:9216
	ds_read_b128 v[226:229], v140 offset:10240
	ds_read_b128 v[230:233], v140 offset:11264
	s_waitcnt lgkmcnt(4)
	v_mfma_f32_16x16x32_bf16 v[2:5], v[194:197], v[178:181], v[2:5]
	v_mfma_f32_16x16x32_bf16 v[6:9], v[198:201], v[178:181], v[6:9]
	v_mfma_f32_16x16x32_bf16 v[10:13], v[202:205], v[178:181], v[10:13]
	v_mfma_f32_16x16x32_bf16 v[14:17], v[206:209], v[178:181], v[14:17]
	v_mfma_f32_16x16x32_bf16 v[18:21], v[194:197], v[182:185], v[18:21]
	v_mfma_f32_16x16x32_bf16 v[22:25], v[198:201], v[182:185], v[22:25]
	v_mfma_f32_16x16x32_bf16 v[26:29], v[202:205], v[182:185], v[26:29]
	v_mfma_f32_16x16x32_bf16 v[30:33], v[206:209], v[182:185], v[30:33]
	v_mfma_f32_16x16x32_bf16 v[34:37], v[194:197], v[186:189], v[34:37]
	v_mfma_f32_16x16x32_bf16 v[38:41], v[198:201], v[186:189], v[38:41]
	v_mfma_f32_16x16x32_bf16 v[42:45], v[202:205], v[186:189], v[42:45]
	v_mfma_f32_16x16x32_bf16 v[46:49], v[206:209], v[186:189], v[46:49]
	v_mfma_f32_16x16x32_bf16 v[50:53], v[194:197], v[190:193], v[50:53]
	v_mfma_f32_16x16x32_bf16 v[54:57], v[198:201], v[190:193], v[54:57]
	v_mfma_f32_16x16x32_bf16 v[58:61], v[202:205], v[190:193], v[58:61]
	v_mfma_f32_16x16x32_bf16 v[62:65], v[206:209], v[190:193], v[62:65]
	s_waitcnt lgkmcnt(0)
	v_mfma_f32_16x16x32_bf16 v[66:69], v[218:221], v[178:181], v[66:69]
	v_mfma_f32_16x16x32_bf16 v[70:73], v[222:225], v[178:181], v[70:73]
	v_mfma_f32_16x16x32_bf16 v[74:77], v[226:229], v[178:181], v[74:77]
	v_mfma_f32_16x16x32_bf16 v[78:81], v[230:233], v[178:181], v[78:81]
	v_mfma_f32_16x16x32_bf16 v[82:85], v[218:221], v[182:185], v[82:85]
	v_mfma_f32_16x16x32_bf16 v[86:89], v[222:225], v[182:185], v[86:89]
	v_mfma_f32_16x16x32_bf16 v[90:93], v[226:229], v[182:185], v[90:93]
	v_mfma_f32_16x16x32_bf16 v[94:97], v[230:233], v[182:185], v[94:97]
	v_mfma_f32_16x16x32_bf16 v[98:101], v[218:221], v[186:189], v[98:101]
	v_mfma_f32_16x16x32_bf16 v[102:105], v[222:225], v[186:189], v[102:105]
	v_mfma_f32_16x16x32_bf16 v[106:109], v[226:229], v[186:189], v[106:109]
	v_mfma_f32_16x16x32_bf16 v[110:113], v[230:233], v[186:189], v[110:113]
	v_mfma_f32_16x16x32_bf16 v[114:117], v[218:221], v[190:193], v[114:117]
	v_mfma_f32_16x16x32_bf16 v[118:121], v[222:225], v[190:193], v[118:121]
	v_mfma_f32_16x16x32_bf16 v[122:125], v[226:229], v[190:193], v[122:125]
	v_mfma_f32_16x16x32_bf16 v[126:129], v[230:233], v[190:193], v[126:129]
.Lg2_a_kdone3:
	s_nop 7
	s_nop 1
	v_mov_b32_e32 v242, v138
	v_mul_f32_e32 v234, 0xbfb8aa3b, v2
	v_mul_f32_e32 v235, 0xbfb8aa3b, v3
	v_mul_f32_e32 v236, 0xbfb8aa3b, v4
	v_mul_f32_e32 v237, 0xbfb8aa3b, v5
	v_exp_f32_e32 v234, v234
	v_exp_f32_e32 v235, v235
	v_exp_f32_e32 v236, v236
	v_exp_f32_e32 v237, v237
	v_add_f32_e32 v234, 1.0, v234
	v_add_f32_e32 v235, 1.0, v235
	v_add_f32_e32 v236, 1.0, v236
	v_add_f32_e32 v237, 1.0, v237
	v_rcp_f32_e32 v234, v234
	v_rcp_f32_e32 v235, v235
	v_rcp_f32_e32 v236, v236
	v_rcp_f32_e32 v237, v237
	v_mul_f32_e32 v234, v2, v234
	v_mul_f32_e32 v235, v3, v235
	v_mul_f32_e32 v236, v4, v236
	v_mul_f32_e32 v237, v5, v237
	v_mul_f32_e32 v234, v10, v234
	v_mul_f32_e32 v235, v11, v235
	v_mul_f32_e32 v236, v12, v236
	v_mul_f32_e32 v237, v13, v237
	v_cvt_pk_bf16_f32 v238, v234, v235
	v_cvt_pk_bf16_f32 v239, v236, v237
	global_store_dwordx2 v242, v[238:239], s[4:5] offset:0
	v_mul_f32_e32 v234, 0xbfb8aa3b, v6
	v_mul_f32_e32 v235, 0xbfb8aa3b, v7
	v_mul_f32_e32 v236, 0xbfb8aa3b, v8
	v_mul_f32_e32 v237, 0xbfb8aa3b, v9
	v_exp_f32_e32 v234, v234
	v_exp_f32_e32 v235, v235
	v_exp_f32_e32 v236, v236
	v_exp_f32_e32 v237, v237
	v_add_f32_e32 v234, 1.0, v234
	v_add_f32_e32 v235, 1.0, v235
	v_add_f32_e32 v236, 1.0, v236
	v_add_f32_e32 v237, 1.0, v237
	v_rcp_f32_e32 v234, v234
	v_rcp_f32_e32 v235, v235
	v_rcp_f32_e32 v236, v236
	v_rcp_f32_e32 v237, v237
	v_mul_f32_e32 v234, v6, v234
	v_mul_f32_e32 v235, v7, v235
	v_mul_f32_e32 v236, v8, v236
	v_mul_f32_e32 v237, v9, v237
	v_mul_f32_e32 v234, v14, v234
	v_mul_f32_e32 v235, v15, v235
	v_mul_f32_e32 v236, v16, v236
	v_mul_f32_e32 v237, v17, v237
	v_cvt_pk_bf16_f32 v240, v234, v235
	v_cvt_pk_bf16_f32 v241, v236, v237
	global_store_dwordx2 v242, v[240:241], s[4:5] offset:32
	v_mul_f32_e32 v234, 0xbfb8aa3b, v66
	v_mul_f32_e32 v235, 0xbfb8aa3b, v67
	v_mul_f32_e32 v236, 0xbfb8aa3b, v68
	v_mul_f32_e32 v237, 0xbfb8aa3b, v69
	v_exp_f32_e32 v234, v234
	v_exp_f32_e32 v235, v235
	v_exp_f32_e32 v236, v236
	v_exp_f32_e32 v237, v237
	v_add_f32_e32 v234, 1.0, v234
	v_add_f32_e32 v235, 1.0, v235
	v_add_f32_e32 v236, 1.0, v236
	v_add_f32_e32 v237, 1.0, v237
	v_rcp_f32_e32 v234, v234
	v_rcp_f32_e32 v235, v235
	v_rcp_f32_e32 v236, v236
	v_rcp_f32_e32 v237, v237
	v_mul_f32_e32 v234, v66, v234
	v_mul_f32_e32 v235, v67, v235
	v_mul_f32_e32 v236, v68, v236
	v_mul_f32_e32 v237, v69, v237
	v_mul_f32_e32 v234, v74, v234
	v_mul_f32_e32 v235, v75, v235
	v_mul_f32_e32 v236, v76, v236
	v_mul_f32_e32 v237, v77, v237
	v_cvt_pk_bf16_f32 v238, v234, v235
	v_cvt_pk_bf16_f32 v239, v236, v237
	global_store_dwordx2 v242, v[238:239], s[4:5] offset:128
	v_mul_f32_e32 v234, 0xbfb8aa3b, v70
	v_mul_f32_e32 v235, 0xbfb8aa3b, v71
	v_mul_f32_e32 v236, 0xbfb8aa3b, v72
	v_mul_f32_e32 v237, 0xbfb8aa3b, v73
	v_exp_f32_e32 v234, v234
	v_exp_f32_e32 v235, v235
	v_exp_f32_e32 v236, v236
	v_exp_f32_e32 v237, v237
	v_add_f32_e32 v234, 1.0, v234
	v_add_f32_e32 v235, 1.0, v235
	v_add_f32_e32 v236, 1.0, v236
	v_add_f32_e32 v237, 1.0, v237
	v_rcp_f32_e32 v234, v234
	v_rcp_f32_e32 v235, v235
	v_rcp_f32_e32 v236, v236
	v_rcp_f32_e32 v237, v237
	v_mul_f32_e32 v234, v70, v234
	v_mul_f32_e32 v235, v71, v235
	v_mul_f32_e32 v236, v72, v236
	v_mul_f32_e32 v237, v73, v237
	v_mul_f32_e32 v234, v78, v234
	v_mul_f32_e32 v235, v79, v235
	v_mul_f32_e32 v236, v80, v236
	v_mul_f32_e32 v237, v81, v237
	v_cvt_pk_bf16_f32 v240, v234, v235
	v_cvt_pk_bf16_f32 v241, v236, v237
	global_store_dwordx2 v242, v[240:241], s[4:5] offset:160
	v_add_u32_e32 v242, 0x16000, v242
	v_mul_f32_e32 v234, 0xbfb8aa3b, v18
	v_mul_f32_e32 v235, 0xbfb8aa3b, v19
	v_mul_f32_e32 v236, 0xbfb8aa3b, v20
	v_mul_f32_e32 v237, 0xbfb8aa3b, v21
	v_exp_f32_e32 v234, v234
	v_exp_f32_e32 v235, v235
	v_exp_f32_e32 v236, v236
	v_exp_f32_e32 v237, v237
	v_add_f32_e32 v234, 1.0, v234
	v_add_f32_e32 v235, 1.0, v235
	v_add_f32_e32 v236, 1.0, v236
	v_add_f32_e32 v237, 1.0, v237
	v_rcp_f32_e32 v234, v234
	v_rcp_f32_e32 v235, v235
	v_rcp_f32_e32 v236, v236
	v_rcp_f32_e32 v237, v237
	v_mul_f32_e32 v234, v18, v234
	v_mul_f32_e32 v235, v19, v235
	v_mul_f32_e32 v236, v20, v236
	v_mul_f32_e32 v237, v21, v237
	v_mul_f32_e32 v234, v26, v234
	v_mul_f32_e32 v235, v27, v235
	v_mul_f32_e32 v236, v28, v236
	v_mul_f32_e32 v237, v29, v237
	v_cvt_pk_bf16_f32 v238, v234, v235
	v_cvt_pk_bf16_f32 v239, v236, v237
	global_store_dwordx2 v242, v[238:239], s[4:5] offset:0
	v_mul_f32_e32 v234, 0xbfb8aa3b, v22
	v_mul_f32_e32 v235, 0xbfb8aa3b, v23
	v_mul_f32_e32 v236, 0xbfb8aa3b, v24
	v_mul_f32_e32 v237, 0xbfb8aa3b, v25
	v_exp_f32_e32 v234, v234
	v_exp_f32_e32 v235, v235
	v_exp_f32_e32 v236, v236
	v_exp_f32_e32 v237, v237
	v_add_f32_e32 v234, 1.0, v234
	v_add_f32_e32 v235, 1.0, v235
	v_add_f32_e32 v236, 1.0, v236
	v_add_f32_e32 v237, 1.0, v237
	v_rcp_f32_e32 v234, v234
	v_rcp_f32_e32 v235, v235
	v_rcp_f32_e32 v236, v236
	v_rcp_f32_e32 v237, v237
	v_mul_f32_e32 v234, v22, v234
	v_mul_f32_e32 v235, v23, v235
	v_mul_f32_e32 v236, v24, v236
	v_mul_f32_e32 v237, v25, v237
	v_mul_f32_e32 v234, v30, v234
	v_mul_f32_e32 v235, v31, v235
	v_mul_f32_e32 v236, v32, v236
	v_mul_f32_e32 v237, v33, v237
	v_cvt_pk_bf16_f32 v240, v234, v235
	v_cvt_pk_bf16_f32 v241, v236, v237
	global_store_dwordx2 v242, v[240:241], s[4:5] offset:32
	v_mul_f32_e32 v234, 0xbfb8aa3b, v82
	v_mul_f32_e32 v235, 0xbfb8aa3b, v83
	v_mul_f32_e32 v236, 0xbfb8aa3b, v84
	v_mul_f32_e32 v237, 0xbfb8aa3b, v85
	v_exp_f32_e32 v234, v234
	v_exp_f32_e32 v235, v235
	v_exp_f32_e32 v236, v236
	v_exp_f32_e32 v237, v237
	v_add_f32_e32 v234, 1.0, v234
	v_add_f32_e32 v235, 1.0, v235
	v_add_f32_e32 v236, 1.0, v236
	v_add_f32_e32 v237, 1.0, v237
	v_rcp_f32_e32 v234, v234
	v_rcp_f32_e32 v235, v235
	v_rcp_f32_e32 v236, v236
	v_rcp_f32_e32 v237, v237
	v_mul_f32_e32 v234, v82, v234
	v_mul_f32_e32 v235, v83, v235
	v_mul_f32_e32 v236, v84, v236
	v_mul_f32_e32 v237, v85, v237
	v_mul_f32_e32 v234, v90, v234
	v_mul_f32_e32 v235, v91, v235
	v_mul_f32_e32 v236, v92, v236
	v_mul_f32_e32 v237, v93, v237
	v_cvt_pk_bf16_f32 v238, v234, v235
	v_cvt_pk_bf16_f32 v239, v236, v237
	global_store_dwordx2 v242, v[238:239], s[4:5] offset:128
	v_mul_f32_e32 v234, 0xbfb8aa3b, v86
	v_mul_f32_e32 v235, 0xbfb8aa3b, v87
	v_mul_f32_e32 v236, 0xbfb8aa3b, v88
	v_mul_f32_e32 v237, 0xbfb8aa3b, v89
	v_exp_f32_e32 v234, v234
	v_exp_f32_e32 v235, v235
	v_exp_f32_e32 v236, v236
	v_exp_f32_e32 v237, v237
	v_add_f32_e32 v234, 1.0, v234
	v_add_f32_e32 v235, 1.0, v235
	v_add_f32_e32 v236, 1.0, v236
	v_add_f32_e32 v237, 1.0, v237
	v_rcp_f32_e32 v234, v234
	v_rcp_f32_e32 v235, v235
	v_rcp_f32_e32 v236, v236
	v_rcp_f32_e32 v237, v237
	v_mul_f32_e32 v234, v86, v234
	v_mul_f32_e32 v235, v87, v235
	v_mul_f32_e32 v236, v88, v236
	v_mul_f32_e32 v237, v89, v237
	v_mul_f32_e32 v234, v94, v234
	v_mul_f32_e32 v235, v95, v235
	v_mul_f32_e32 v236, v96, v236
	v_mul_f32_e32 v237, v97, v237
	v_cvt_pk_bf16_f32 v240, v234, v235
	v_cvt_pk_bf16_f32 v241, v236, v237
	global_store_dwordx2 v242, v[240:241], s[4:5] offset:160
	v_add_u32_e32 v242, 0x16000, v242
	v_mul_f32_e32 v234, 0xbfb8aa3b, v34
	v_mul_f32_e32 v235, 0xbfb8aa3b, v35
	v_mul_f32_e32 v236, 0xbfb8aa3b, v36
	v_mul_f32_e32 v237, 0xbfb8aa3b, v37
	v_exp_f32_e32 v234, v234
	v_exp_f32_e32 v235, v235
	v_exp_f32_e32 v236, v236
	v_exp_f32_e32 v237, v237
	v_add_f32_e32 v234, 1.0, v234
	v_add_f32_e32 v235, 1.0, v235
	v_add_f32_e32 v236, 1.0, v236
	v_add_f32_e32 v237, 1.0, v237
	v_rcp_f32_e32 v234, v234
	v_rcp_f32_e32 v235, v235
	v_rcp_f32_e32 v236, v236
	v_rcp_f32_e32 v237, v237
	v_mul_f32_e32 v234, v34, v234
	v_mul_f32_e32 v235, v35, v235
	v_mul_f32_e32 v236, v36, v236
	v_mul_f32_e32 v237, v37, v237
	v_mul_f32_e32 v234, v42, v234
	v_mul_f32_e32 v235, v43, v235
	v_mul_f32_e32 v236, v44, v236
	v_mul_f32_e32 v237, v45, v237
	v_cvt_pk_bf16_f32 v238, v234, v235
	v_cvt_pk_bf16_f32 v239, v236, v237
	global_store_dwordx2 v242, v[238:239], s[4:5] offset:0
	v_mul_f32_e32 v234, 0xbfb8aa3b, v38
	v_mul_f32_e32 v235, 0xbfb8aa3b, v39
	v_mul_f32_e32 v236, 0xbfb8aa3b, v40
	v_mul_f32_e32 v237, 0xbfb8aa3b, v41
	v_exp_f32_e32 v234, v234
	v_exp_f32_e32 v235, v235
	v_exp_f32_e32 v236, v236
	v_exp_f32_e32 v237, v237
	v_add_f32_e32 v234, 1.0, v234
	v_add_f32_e32 v235, 1.0, v235
	v_add_f32_e32 v236, 1.0, v236
	v_add_f32_e32 v237, 1.0, v237
	v_rcp_f32_e32 v234, v234
	v_rcp_f32_e32 v235, v235
	v_rcp_f32_e32 v236, v236
	v_rcp_f32_e32 v237, v237
	v_mul_f32_e32 v234, v38, v234
	v_mul_f32_e32 v235, v39, v235
	v_mul_f32_e32 v236, v40, v236
	v_mul_f32_e32 v237, v41, v237
	v_mul_f32_e32 v234, v46, v234
	v_mul_f32_e32 v235, v47, v235
	v_mul_f32_e32 v236, v48, v236
	v_mul_f32_e32 v237, v49, v237
	v_cvt_pk_bf16_f32 v240, v234, v235
	v_cvt_pk_bf16_f32 v241, v236, v237
	global_store_dwordx2 v242, v[240:241], s[4:5] offset:32
	v_mul_f32_e32 v234, 0xbfb8aa3b, v98
	v_mul_f32_e32 v235, 0xbfb8aa3b, v99
	v_mul_f32_e32 v236, 0xbfb8aa3b, v100
	v_mul_f32_e32 v237, 0xbfb8aa3b, v101
	v_exp_f32_e32 v234, v234
	v_exp_f32_e32 v235, v235
	v_exp_f32_e32 v236, v236
	v_exp_f32_e32 v237, v237
	v_add_f32_e32 v234, 1.0, v234
	v_add_f32_e32 v235, 1.0, v235
	v_add_f32_e32 v236, 1.0, v236
	v_add_f32_e32 v237, 1.0, v237
	v_rcp_f32_e32 v234, v234
	v_rcp_f32_e32 v235, v235
	v_rcp_f32_e32 v236, v236
	v_rcp_f32_e32 v237, v237
	v_mul_f32_e32 v234, v98, v234
	v_mul_f32_e32 v235, v99, v235
	v_mul_f32_e32 v236, v100, v236
	v_mul_f32_e32 v237, v101, v237
	v_mul_f32_e32 v234, v106, v234
	v_mul_f32_e32 v235, v107, v235
	v_mul_f32_e32 v236, v108, v236
	v_mul_f32_e32 v237, v109, v237
	v_cvt_pk_bf16_f32 v238, v234, v235
	v_cvt_pk_bf16_f32 v239, v236, v237
	global_store_dwordx2 v242, v[238:239], s[4:5] offset:128
	v_mul_f32_e32 v234, 0xbfb8aa3b, v102
	v_mul_f32_e32 v235, 0xbfb8aa3b, v103
	v_mul_f32_e32 v236, 0xbfb8aa3b, v104
	v_mul_f32_e32 v237, 0xbfb8aa3b, v105
	v_exp_f32_e32 v234, v234
	v_exp_f32_e32 v235, v235
	v_exp_f32_e32 v236, v236
	v_exp_f32_e32 v237, v237
	v_add_f32_e32 v234, 1.0, v234
	v_add_f32_e32 v235, 1.0, v235
	v_add_f32_e32 v236, 1.0, v236
	v_add_f32_e32 v237, 1.0, v237
	v_rcp_f32_e32 v234, v234
	v_rcp_f32_e32 v235, v235
	v_rcp_f32_e32 v236, v236
	v_rcp_f32_e32 v237, v237
	v_mul_f32_e32 v234, v102, v234
	v_mul_f32_e32 v235, v103, v235
	v_mul_f32_e32 v236, v104, v236
	v_mul_f32_e32 v237, v105, v237
	v_mul_f32_e32 v234, v110, v234
	v_mul_f32_e32 v235, v111, v235
	v_mul_f32_e32 v236, v112, v236
	v_mul_f32_e32 v237, v113, v237
	v_cvt_pk_bf16_f32 v240, v234, v235
	v_cvt_pk_bf16_f32 v241, v236, v237
	global_store_dwordx2 v242, v[240:241], s[4:5] offset:160
	v_add_u32_e32 v242, 0x16000, v242
	v_mul_f32_e32 v234, 0xbfb8aa3b, v50
	v_mul_f32_e32 v235, 0xbfb8aa3b, v51
	v_mul_f32_e32 v236, 0xbfb8aa3b, v52
	v_mul_f32_e32 v237, 0xbfb8aa3b, v53
	v_exp_f32_e32 v234, v234
	v_exp_f32_e32 v235, v235
	v_exp_f32_e32 v236, v236
	v_exp_f32_e32 v237, v237
	v_add_f32_e32 v234, 1.0, v234
	v_add_f32_e32 v235, 1.0, v235
	v_add_f32_e32 v236, 1.0, v236
	v_add_f32_e32 v237, 1.0, v237
	v_rcp_f32_e32 v234, v234
	v_rcp_f32_e32 v235, v235
	v_rcp_f32_e32 v236, v236
	v_rcp_f32_e32 v237, v237
	v_mul_f32_e32 v234, v50, v234
	v_mul_f32_e32 v235, v51, v235
	v_mul_f32_e32 v236, v52, v236
	v_mul_f32_e32 v237, v53, v237
	v_mul_f32_e32 v234, v58, v234
	v_mul_f32_e32 v235, v59, v235
	v_mul_f32_e32 v236, v60, v236
	v_mul_f32_e32 v237, v61, v237
	v_cvt_pk_bf16_f32 v238, v234, v235
	v_cvt_pk_bf16_f32 v239, v236, v237
	global_store_dwordx2 v242, v[238:239], s[4:5] offset:0
	v_mul_f32_e32 v234, 0xbfb8aa3b, v54
	v_mul_f32_e32 v235, 0xbfb8aa3b, v55
	v_mul_f32_e32 v236, 0xbfb8aa3b, v56
	v_mul_f32_e32 v237, 0xbfb8aa3b, v57
	v_exp_f32_e32 v234, v234
	v_exp_f32_e32 v235, v235
	v_exp_f32_e32 v236, v236
	v_exp_f32_e32 v237, v237
	v_add_f32_e32 v234, 1.0, v234
	v_add_f32_e32 v235, 1.0, v235
	v_add_f32_e32 v236, 1.0, v236
	v_add_f32_e32 v237, 1.0, v237
	v_rcp_f32_e32 v234, v234
	v_rcp_f32_e32 v235, v235
	v_rcp_f32_e32 v236, v236
	v_rcp_f32_e32 v237, v237
	v_mul_f32_e32 v234, v54, v234
	v_mul_f32_e32 v235, v55, v235
	v_mul_f32_e32 v236, v56, v236
	v_mul_f32_e32 v237, v57, v237
	v_mul_f32_e32 v234, v62, v234
	v_mul_f32_e32 v235, v63, v235
	v_mul_f32_e32 v236, v64, v236
	v_mul_f32_e32 v237, v65, v237
	v_cvt_pk_bf16_f32 v240, v234, v235
	v_cvt_pk_bf16_f32 v241, v236, v237
	global_store_dwordx2 v242, v[240:241], s[4:5] offset:32
	v_mul_f32_e32 v234, 0xbfb8aa3b, v114
	v_mul_f32_e32 v235, 0xbfb8aa3b, v115
	v_mul_f32_e32 v236, 0xbfb8aa3b, v116
	v_mul_f32_e32 v237, 0xbfb8aa3b, v117
	v_exp_f32_e32 v234, v234
	v_exp_f32_e32 v235, v235
	v_exp_f32_e32 v236, v236
	v_exp_f32_e32 v237, v237
	v_add_f32_e32 v234, 1.0, v234
	v_add_f32_e32 v235, 1.0, v235
	v_add_f32_e32 v236, 1.0, v236
	v_add_f32_e32 v237, 1.0, v237
	v_rcp_f32_e32 v234, v234
	v_rcp_f32_e32 v235, v235
	v_rcp_f32_e32 v236, v236
	v_rcp_f32_e32 v237, v237
	v_mul_f32_e32 v234, v114, v234
	v_mul_f32_e32 v235, v115, v235
	v_mul_f32_e32 v236, v116, v236
	v_mul_f32_e32 v237, v117, v237
	v_mul_f32_e32 v234, v122, v234
	v_mul_f32_e32 v235, v123, v235
	v_mul_f32_e32 v236, v124, v236
	v_mul_f32_e32 v237, v125, v237
	v_cvt_pk_bf16_f32 v238, v234, v235
	v_cvt_pk_bf16_f32 v239, v236, v237
	global_store_dwordx2 v242, v[238:239], s[4:5] offset:128
	v_mul_f32_e32 v234, 0xbfb8aa3b, v118
	v_mul_f32_e32 v235, 0xbfb8aa3b, v119
	v_mul_f32_e32 v236, 0xbfb8aa3b, v120
	v_mul_f32_e32 v237, 0xbfb8aa3b, v121
	v_exp_f32_e32 v234, v234
	v_exp_f32_e32 v235, v235
	v_exp_f32_e32 v236, v236
	v_exp_f32_e32 v237, v237
	v_add_f32_e32 v234, 1.0, v234
	v_add_f32_e32 v235, 1.0, v235
	v_add_f32_e32 v236, 1.0, v236
	v_add_f32_e32 v237, 1.0, v237
	v_rcp_f32_e32 v234, v234
	v_rcp_f32_e32 v235, v235
	v_rcp_f32_e32 v236, v236
	v_rcp_f32_e32 v237, v237
	v_mul_f32_e32 v234, v118, v234
	v_mul_f32_e32 v235, v119, v235
	v_mul_f32_e32 v236, v120, v236
	v_mul_f32_e32 v237, v121, v237
	v_mul_f32_e32 v234, v126, v234
	v_mul_f32_e32 v235, v127, v235
	v_mul_f32_e32 v236, v128, v236
	v_mul_f32_e32 v237, v129, v237
	v_cvt_pk_bf16_f32 v240, v234, v235
	v_cvt_pk_bf16_f32 v241, v236, v237
	global_store_dwordx2 v242, v[240:241], s[4:5] offset:160
	s_add_u32 s10, s10, 32
	s_cmp_lt_u32 s10, 64
	s_cbranch_scc1 .Lg2_a_item1
	s_cmp_lt_u32 s15, 8
	s_cbranch_scc0 .Lg2_a_noleft6
	s_lshr_b32 s12, s15, 2
	s_add_u32 s12, s12, 4
	s_mov_b32 s11, 10
	s_and_b32 s16, s15, 3
	s_lshl_b32 s16, s16, 6
	s_and_b32 s17, s14, 3
	s_mul_i32 s17, s17, 6
	s_add_u32 s12, s12, s17
	s_lshl_b32 s12, s12, 8
	s_add_u32 s12, s12, s16
	s_lshr_b32 s17, s14, 2
	s_mul_i32 s17, s17, 22
	s_lshl_b32 s11, s11, 1
	s_add_u32 s11, s11, s17
	s_lshl_b32 s16, s12, 11
	s_add_u32 s0, s24, s16
	s_addc_u32 s1, s25, 0
	s_lshl_b32 s16, s11, 18
	s_add_u32 s2, s40, s16
	s_addc_u32 s3, s41, 0
	s_mul_i32 s16, s12, 0x1600
	s_lshl_b32 s17, s11, 7
	s_add_u32 s16, s16, s17
	s_add_u32 s4, s26, s16
	s_addc_u32 s5, s27, 0
	v_lshrrev_b32_e32 v141, 7, v142
	v_lshlrev_b32_e32 v139, 12, v141
	v_sub_u32_e32 v134, v134, v139
	v_lshl_add_u32 v134, v141, 10, v134
	v_mul_u32_u24_e32 v139, 0x42000, v141
	v_sub_u32_e32 v138, v138, v139
	v_lshrrev_b32_e32 v141, 8, v142
	v_lshlrev_b32_e32 v141, 17, v141
	v_sub_u32_e32 v141, v136, v141
	s_and_b32 s17, s6, 0xfff
	s_add_u32 m0, s17, 0x0
	s_nop 0
	global_load_lds_dwordx4 v141, s[0:1]
	s_add_u32 m0, s6, 0x4000
	s_nop 0
	global_load_lds_dwordx4 v136, s[2:3]
	s_add_u32 m0, s6, 0x6000
	s_nop 0
	global_load_lds_dwordx4 v137, s[2:3]
	s_add_u32 s0, s0, 64
	s_addc_u32 s1, s1, 0
	s_add_u32 s2, s2, 64
	s_addc_u32 s3, s3, 0
	s_add_u32 m0, s17, 0x8000
	s_nop 0
	global_load_lds_dwordx4 v141, s[0:1]
	s_add_u32 m0, s6, 0xc000
	s_nop 0
	global_load_lds_dwordx4 v136, s[2:3]
	s_add_u32 m0, s6, 0xe000
	s_nop 0
	global_load_lds_dwordx4 v137, s[2:3]
	s_add_u32 s0, s0, 64
	s_addc_u32 s1, s1, 0
	s_add_u32 s2, s2, 64
	s_addc_u32 s3, s3, 0
	s_add_u32 m0, s17, 0x10000
	s_nop 0
	global_load_lds_dwordx4 v141, s[0:1]
	s_add_u32 m0, s6, 0x14000
	s_nop 0
	global_load_lds_dwordx4 v136, s[2:3]
	s_add_u32 m0, s6, 0x16000
	s_nop 0
	global_load_lds_dwordx4 v137, s[2:3]
	s_add_u32 s0, s0, 64
	s_addc_u32 s1, s1, 0
	s_add_u32 s2, s2, 64
	s_addc_u32 s3, s3, 0
	v_mov_b32_e32 v2, 0
	v_mov_b32_e32 v3, 0
	v_mov_b32_e32 v4, 0
	v_mov_b32_e32 v5, 0
	v_mov_b32_e32 v6, 0
	v_mov_b32_e32 v7, 0
	v_mov_b32_e32 v8, 0
	v_mov_b32_e32 v9, 0
	v_mov_b32_e32 v10, 0
	v_mov_b32_e32 v11, 0
	v_mov_b32_e32 v12, 0
	v_mov_b32_e32 v13, 0
	v_mov_b32_e32 v14, 0
	v_mov_b32_e32 v15, 0
	v_mov_b32_e32 v16, 0
	v_mov_b32_e32 v17, 0
	v_mov_b32_e32 v66, 0
	v_mov_b32_e32 v67, 0
	v_mov_b32_e32 v68, 0
	v_mov_b32_e32 v69, 0
	v_mov_b32_e32 v70, 0
	v_mov_b32_e32 v71, 0
	v_mov_b32_e32 v72, 0
	v_mov_b32_e32 v73, 0
	v_mov_b32_e32 v74, 0
	v_mov_b32_e32 v75, 0
	v_mov_b32_e32 v76, 0
	v_mov_b32_e32 v77, 0
	v_mov_b32_e32 v78, 0
	v_mov_b32_e32 v79, 0
	v_mov_b32_e32 v80, 0
	v_mov_b32_e32 v81, 0
	s_bitcmp1_b32 s6, 12
	s_cbranch_scc1 .Lg2_a_grpB7
	s_mov_b32 s7, 7
.Lg2_a_klA9:
	s_waitcnt vmcnt(6)
	s_barrier
	v_add_u32_e32 v139, 0x0, v134
	v_add_u32_e32 v140, 0x0, v135
	ds_read_b128 v[162:165], v139 offset:0
	ds_read_b128 v[194:197], v140 offset:0
	ds_read_b128 v[198:201], v140 offset:1024
	ds_read_b128 v[202:205], v140 offset:2048
	ds_read_b128 v[206:209], v140 offset:3072
	ds_read_b128 v[218:221], v140 offset:8192
	ds_read_b128 v[222:225], v140 offset:9216
	ds_read_b128 v[226:229], v140 offset:10240
	ds_read_b128 v[230:233], v140 offset:11264
	s_add_u32 m0, s17, 0x18000
	s_nop 0
	global_load_lds_dwordx4 v141, s[0:1]
	s_add_u32 m0, s6, 0x1c000
	s_nop 0
	global_load_lds_dwordx4 v136, s[2:3]
	s_add_u32 m0, s6, 0x1e000
	s_nop 0
	global_load_lds_dwordx4 v137, s[2:3]
	s_add_u32 s0, s0, 64
	s_addc_u32 s1, s1, 0
	s_add_u32 s2, s2, 64
	s_addc_u32 s3, s3, 0
	s_waitcnt lgkmcnt(4)
	v_mfma_f32_16x16x32_bf16 v[2:5], v[194:197], v[162:165], v[2:5]
	v_mfma_f32_16x16x32_bf16 v[6:9], v[198:201], v[162:165], v[6:9]
	v_mfma_f32_16x16x32_bf16 v[10:13], v[202:205], v[162:165], v[10:13]
	v_mfma_f32_16x16x32_bf16 v[14:17], v[206:209], v[162:165], v[14:17]
	s_waitcnt lgkmcnt(0)
	v_mfma_f32_16x16x32_bf16 v[66:69], v[218:221], v[162:165], v[66:69]
	v_mfma_f32_16x16x32_bf16 v[70:73], v[222:225], v[162:165], v[70:73]
	v_mfma_f32_16x16x32_bf16 v[74:77], v[226:229], v[162:165], v[74:77]
	v_mfma_f32_16x16x32_bf16 v[78:81], v[230:233], v[162:165], v[78:81]
	s_waitcnt vmcnt(6)
	s_barrier
	v_add_u32_e32 v139, 0x8000, v134
	v_add_u32_e32 v140, 0x8000, v135
	ds_read_b128 v[162:165], v139 offset:0
	ds_read_b128 v[194:197], v140 offset:0
	ds_read_b128 v[198:201], v140 offset:1024
	ds_read_b128 v[202:205], v140 offset:2048
	ds_read_b128 v[206:209], v140 offset:3072
	ds_read_b128 v[218:221], v140 offset:8192
	ds_read_b128 v[222:225], v140 offset:9216
	ds_read_b128 v[226:229], v140 offset:10240
	ds_read_b128 v[230:233], v140 offset:11264
	s_add_u32 m0, s17, 0x0
	s_nop 0
	global_load_lds_dwordx4 v141, s[0:1]
	s_add_u32 m0, s6, 0x4000
	s_nop 0
	global_load_lds_dwordx4 v136, s[2:3]
	s_add_u32 m0, s6, 0x6000
	s_nop 0
	global_load_lds_dwordx4 v137, s[2:3]
	s_add_u32 s0, s0, 64
	s_addc_u32 s1, s1, 0
	s_add_u32 s2, s2, 64
	s_addc_u32 s3, s3, 0
	s_waitcnt lgkmcnt(4)
	v_mfma_f32_16x16x32_bf16 v[2:5], v[194:197], v[162:165], v[2:5]
	v_mfma_f32_16x16x32_bf16 v[6:9], v[198:201], v[162:165], v[6:9]
	v_mfma_f32_16x16x32_bf16 v[10:13], v[202:205], v[162:165], v[10:13]
	v_mfma_f32_16x16x32_bf16 v[14:17], v[206:209], v[162:165], v[14:17]
	s_waitcnt lgkmcnt(0)
	v_mfma_f32_16x16x32_bf16 v[66:69], v[218:221], v[162:165], v[66:69]
	v_mfma_f32_16x16x32_bf16 v[70:73], v[222:225], v[162:165], v[70:73]
	v_mfma_f32_16x16x32_bf16 v[74:77], v[226:229], v[162:165], v[74:77]
	v_mfma_f32_16x16x32_bf16 v[78:81], v[230:233], v[162:165], v[78:81]
	s_waitcnt vmcnt(6)
	s_barrier
	v_add_u32_e32 v139, 0x10000, v134
	v_add_u32_e32 v140, 0x10000, v135
	ds_read_b128 v[162:165], v139 offset:0
	ds_read_b128 v[194:197], v140 offset:0
	ds_read_b128 v[198:201], v140 offset:1024
	ds_read_b128 v[202:205], v140 offset:2048
	ds_read_b128 v[206:209], v140 offset:3072
	ds_read_b128 v[218:221], v140 offset:8192
	ds_read_b128 v[222:225], v140 offset:9216
	ds_read_b128 v[226:229], v140 offset:10240
	ds_read_b128 v[230:233], v140 offset:11264
	s_add_u32 m0, s17, 0x8000
	s_nop 0
	global_load_lds_dwordx4 v141, s[0:1]
	s_add_u32 m0, s6, 0xc000
	s_nop 0
	global_load_lds_dwordx4 v136, s[2:3]
	s_add_u32 m0, s6, 0xe000
	s_nop 0
	global_load_lds_dwordx4 v137, s[2:3]
	s_add_u32 s0, s0, 64
	s_addc_u32 s1, s1, 0
	s_add_u32 s2, s2, 64
	s_addc_u32 s3, s3, 0
	s_waitcnt lgkmcnt(4)
	v_mfma_f32_16x16x32_bf16 v[2:5], v[194:197], v[162:165], v[2:5]
	v_mfma_f32_16x16x32_bf16 v[6:9], v[198:201], v[162:165], v[6:9]
	v_mfma_f32_16x16x32_bf16 v[10:13], v[202:205], v[162:165], v[10:13]
	v_mfma_f32_16x16x32_bf16 v[14:17], v[206:209], v[162:165], v[14:17]
	s_waitcnt lgkmcnt(0)
	v_mfma_f32_16x16x32_bf16 v[66:69], v[218:221], v[162:165], v[66:69]
	v_mfma_f32_16x16x32_bf16 v[70:73], v[222:225], v[162:165], v[70:73]
	v_mfma_f32_16x16x32_bf16 v[74:77], v[226:229], v[162:165], v[74:77]
	v_mfma_f32_16x16x32_bf16 v[78:81], v[230:233], v[162:165], v[78:81]
	s_waitcnt vmcnt(6)
	s_barrier
	v_add_u32_e32 v139, 0x18000, v134
	v_add_u32_e32 v140, 0x18000, v135
	ds_read_b128 v[162:165], v139 offset:0
	ds_read_b128 v[194:197], v140 offset:0
	ds_read_b128 v[198:201], v140 offset:1024
	ds_read_b128 v[202:205], v140 offset:2048
	ds_read_b128 v[206:209], v140 offset:3072
	ds_read_b128 v[218:221], v140 offset:8192
	ds_read_b128 v[222:225], v140 offset:9216
	ds_read_b128 v[226:229], v140 offset:10240
	ds_read_b128 v[230:233], v140 offset:11264
	s_add_u32 m0, s17, 0x10000
	s_nop 0
	global_load_lds_dwordx4 v141, s[0:1]
	s_add_u32 m0, s6, 0x14000
	s_nop 0
	global_load_lds_dwordx4 v136, s[2:3]
	s_add_u32 m0, s6, 0x16000
	s_nop 0
	global_load_lds_dwordx4 v137, s[2:3]
	s_add_u32 s0, s0, 64
	s_addc_u32 s1, s1, 0
	s_add_u32 s2, s2, 64
	s_addc_u32 s3, s3, 0
	s_waitcnt lgkmcnt(4)
	v_mfma_f32_16x16x32_bf16 v[2:5], v[194:197], v[162:165], v[2:5]
	v_mfma_f32_16x16x32_bf16 v[6:9], v[198:201], v[162:165], v[6:9]
	v_mfma_f32_16x16x32_bf16 v[10:13], v[202:205], v[162:165], v[10:13]
	v_mfma_f32_16x16x32_bf16 v[14:17], v[206:209], v[162:165], v[14:17]
	s_waitcnt lgkmcnt(0)
	v_mfma_f32_16x16x32_bf16 v[66:69], v[218:221], v[162:165], v[66:69]
	v_mfma_f32_16x16x32_bf16 v[70:73], v[222:225], v[162:165], v[70:73]
	v_mfma_f32_16x16x32_bf16 v[74:77], v[226:229], v[162:165], v[74:77]
	v_mfma_f32_16x16x32_bf16 v[78:81], v[230:233], v[162:165], v[78:81]
	s_sub_u32 s7, s7, 1
	s_cmp_lg_u32 s7, 0
	s_cbranch_scc1 .Lg2_a_klA9
	s_waitcnt vmcnt(6)
	s_barrier
	v_add_u32_e32 v139, 0x0, v134
	v_add_u32_e32 v140, 0x0, v135
	ds_read_b128 v[162:165], v139 offset:0
	ds_read_b128 v[194:197], v140 offset:0
	ds_read_b128 v[198:201], v140 offset:1024
	ds_read_b128 v[202:205], v140 offset:2048
	ds_read_b128 v[206:209], v140 offset:3072
	ds_read_b128 v[218:221], v140 offset:8192
	ds_read_b128 v[222:225], v140 offset:9216
	ds_read_b128 v[226:229], v140 offset:10240
	ds_read_b128 v[230:233], v140 offset:11264
	s_add_u32 m0, s17, 0x18000
	s_nop 0
	global_load_lds_dwordx4 v141, s[0:1]
	s_add_u32 m0, s6, 0x1c000
	s_nop 0
	global_load_lds_dwordx4 v136, s[2:3]
	s_add_u32 m0, s6, 0x1e000
	s_nop 0
	global_load_lds_dwordx4 v137, s[2:3]
	s_add_u32 s0, s0, 64
	s_addc_u32 s1, s1, 0
	s_add_u32 s2, s2, 64
	s_addc_u32 s3, s3, 0
	s_waitcnt lgkmcnt(4)
	v_mfma_f32_16x16x32_bf16 v[2:5], v[194:197], v[162:165], v[2:5]
	v_mfma_f32_16x16x32_bf16 v[6:9], v[198:201], v[162:165], v[6:9]
	v_mfma_f32_16x16x32_bf16 v[10:13], v[202:205], v[162:165], v[10:13]
	v_mfma_f32_16x16x32_bf16 v[14:17], v[206:209], v[162:165], v[14:17]
	s_waitcnt lgkmcnt(0)
	v_mfma_f32_16x16x32_bf16 v[66:69], v[218:221], v[162:165], v[66:69]
	v_mfma_f32_16x16x32_bf16 v[70:73], v[222:225], v[162:165], v[70:73]
	v_mfma_f32_16x16x32_bf16 v[74:77], v[226:229], v[162:165], v[74:77]
	v_mfma_f32_16x16x32_bf16 v[78:81], v[230:233], v[162:165], v[78:81]
	s_waitcnt vmcnt(6)
	s_barrier
	v_add_u32_e32 v139, 0x8000, v134
	v_add_u32_e32 v140, 0x8000, v135
	ds_read_b128 v[162:165], v139 offset:0
	ds_read_b128 v[194:197], v140 offset:0
	ds_read_b128 v[198:201], v140 offset:1024
	ds_read_b128 v[202:205], v140 offset:2048
	ds_read_b128 v[206:209], v140 offset:3072
	ds_read_b128 v[218:221], v140 offset:8192
	ds_read_b128 v[222:225], v140 offset:9216
	ds_read_b128 v[226:229], v140 offset:10240
	ds_read_b128 v[230:233], v140 offset:11264
	s_waitcnt lgkmcnt(4)
	v_mfma_f32_16x16x32_bf16 v[2:5], v[194:197], v[162:165], v[2:5]
	v_mfma_f32_16x16x32_bf16 v[6:9], v[198:201], v[162:165], v[6:9]
	v_mfma_f32_16x16x32_bf16 v[10:13], v[202:205], v[162:165], v[10:13]
	v_mfma_f32_16x16x32_bf16 v[14:17], v[206:209], v[162:165], v[14:17]
	s_waitcnt lgkmcnt(0)
	v_mfma_f32_16x16x32_bf16 v[66:69], v[218:221], v[162:165], v[66:69]
	v_mfma_f32_16x16x32_bf16 v[70:73], v[222:225], v[162:165], v[70:73]
	v_mfma_f32_16x16x32_bf16 v[74:77], v[226:229], v[162:165], v[74:77]
	v_mfma_f32_16x16x32_bf16 v[78:81], v[230:233], v[162:165], v[78:81]
	s_waitcnt vmcnt(3)
	s_barrier
	v_add_u32_e32 v139, 0x10000, v134
	v_add_u32_e32 v140, 0x10000, v135
	ds_read_b128 v[162:165], v139 offset:0
	ds_read_b128 v[194:197], v140 offset:0
	ds_read_b128 v[198:201], v140 offset:1024
	ds_read_b128 v[202:205], v140 offset:2048
	ds_read_b128 v[206:209], v140 offset:3072
	ds_read_b128 v[218:221], v140 offset:8192
	ds_read_b128 v[222:225], v140 offset:9216
	ds_read_b128 v[226:229], v140 offset:10240
	ds_read_b128 v[230:233], v140 offset:11264
	s_waitcnt lgkmcnt(4)
	v_mfma_f32_16x16x32_bf16 v[2:5], v[194:197], v[162:165], v[2:5]
	v_mfma_f32_16x16x32_bf16 v[6:9], v[198:201], v[162:165], v[6:9]
	v_mfma_f32_16x16x32_bf16 v[10:13], v[202:205], v[162:165], v[10:13]
	v_mfma_f32_16x16x32_bf16 v[14:17], v[206:209], v[162:165], v[14:17]
	s_waitcnt lgkmcnt(0)
	v_mfma_f32_16x16x32_bf16 v[66:69], v[218:221], v[162:165], v[66:69]
	v_mfma_f32_16x16x32_bf16 v[70:73], v[222:225], v[162:165], v[70:73]
	v_mfma_f32_16x16x32_bf16 v[74:77], v[226:229], v[162:165], v[74:77]
	v_mfma_f32_16x16x32_bf16 v[78:81], v[230:233], v[162:165], v[78:81]
	s_waitcnt vmcnt(0)
	s_barrier
	v_add_u32_e32 v139, 0x18000, v134
	v_add_u32_e32 v140, 0x18000, v135
	ds_read_b128 v[162:165], v139 offset:0
	ds_read_b128 v[194:197], v140 offset:0
	ds_read_b128 v[198:201], v140 offset:1024
	ds_read_b128 v[202:205], v140 offset:2048
	ds_read_b128 v[206:209], v140 offset:3072
	ds_read_b128 v[218:221], v140 offset:8192
	ds_read_b128 v[222:225], v140 offset:9216
	ds_read_b128 v[226:229], v140 offset:10240
	ds_read_b128 v[230:233], v140 offset:11264
	s_waitcnt lgkmcnt(4)
	v_mfma_f32_16x16x32_bf16 v[2:5], v[194:197], v[162:165], v[2:5]
	v_mfma_f32_16x16x32_bf16 v[6:9], v[198:201], v[162:165], v[6:9]
	v_mfma_f32_16x16x32_bf16 v[10:13], v[202:205], v[162:165], v[10:13]
	v_mfma_f32_16x16x32_bf16 v[14:17], v[206:209], v[162:165], v[14:17]
	s_waitcnt lgkmcnt(0)
	v_mfma_f32_16x16x32_bf16 v[66:69], v[218:221], v[162:165], v[66:69]
	v_mfma_f32_16x16x32_bf16 v[70:73], v[222:225], v[162:165], v[70:73]
	v_mfma_f32_16x16x32_bf16 v[74:77], v[226:229], v[162:165], v[74:77]
	v_mfma_f32_16x16x32_bf16 v[78:81], v[230:233], v[162:165], v[78:81]
	s_branch .Lg2_a_kdone8
.Lg2_a_grpB7:
	v_mov_b32_e32 v178, 0
	v_mov_b32_e32 v179, 0
	v_mov_b32_e32 v180, 0
	v_mov_b32_e32 v181, 0
	v_mov_b32_e32 v218, 0
	v_mov_b32_e32 v219, 0
	v_mov_b32_e32 v220, 0
	v_mov_b32_e32 v221, 0
	v_mov_b32_e32 v222, 0
	v_mov_b32_e32 v223, 0
	v_mov_b32_e32 v224, 0
	v_mov_b32_e32 v225, 0
	v_mov_b32_e32 v226, 0
	v_mov_b32_e32 v227, 0
	v_mov_b32_e32 v228, 0
	v_mov_b32_e32 v229, 0
	v_mov_b32_e32 v230, 0
	v_mov_b32_e32 v231, 0
	v_mov_b32_e32 v232, 0
	v_mov_b32_e32 v233, 0
	s_mov_b32 s7, 7
.Lg2_a_klB10:
	s_waitcnt vmcnt(6)
	s_barrier
	v_add_u32_e32 v139, 0x0, v134
	v_add_u32_e32 v140, 0x0, v135
	ds_read_b128 v[162:165], v139 offset:0
	ds_read_b128 v[194:197], v140 offset:0
	ds_read_b128 v[198:201], v140 offset:1024
	ds_read_b128 v[202:205], v140 offset:2048
	ds_read_b128 v[206:209], v140 offset:3072
	v_mfma_f32_16x16x32_bf16 v[66:69], v[218:221], v[178:181], v[66:69]
	s_add_u32 m0, s17, 0x18000
	s_nop 0
	global_load_lds_dwordx4 v141, s[0:1]
	v_mfma_f32_16x16x32_bf16 v[70:73], v[222:225], v[178:181], v[70:73]
	v_mfma_f32_16x16x32_bf16 v[74:77], v[226:229], v[178:181], v[74:77]
	s_add_u32 m0, s6, 0x1c000
	s_nop 0
	global_load_lds_dwordx4 v136, s[2:3]
	v_mfma_f32_16x16x32_bf16 v[78:81], v[230:233], v[178:181], v[78:81]
	s_add_u32 m0, s6, 0x1e000
	s_nop 0
	global_load_lds_dwordx4 v137, s[2:3]
	s_add_u32 s0, s0, 64
	s_addc_u32 s1, s1, 0
	s_add_u32 s2, s2, 64
	s_addc_u32 s3, s3, 0
	ds_read_b128 v[218:221], v140 offset:8192
	ds_read_b128 v[222:225], v140 offset:9216
	ds_read_b128 v[226:229], v140 offset:10240
	ds_read_b128 v[230:233], v140 offset:11264
	s_waitcnt lgkmcnt(4)
	v_mfma_f32_16x16x32_bf16 v[2:5], v[194:197], v[162:165], v[2:5]
	v_mfma_f32_16x16x32_bf16 v[6:9], v[198:201], v[162:165], v[6:9]
	v_mfma_f32_16x16x32_bf16 v[10:13], v[202:205], v[162:165], v[10:13]
	v_mfma_f32_16x16x32_bf16 v[14:17], v[206:209], v[162:165], v[14:17]
	s_waitcnt lgkmcnt(0)
	s_waitcnt vmcnt(6)
	s_barrier
	v_add_u32_e32 v139, 0x8000, v134
	v_add_u32_e32 v140, 0x8000, v135
	ds_read_b128 v[178:181], v139 offset:0
	ds_read_b128 v[194:197], v140 offset:0
	ds_read_b128 v[198:201], v140 offset:1024
	ds_read_b128 v[202:205], v140 offset:2048
	ds_read_b128 v[206:209], v140 offset:3072
	v_mfma_f32_16x16x32_bf16 v[66:69], v[218:221], v[162:165], v[66:69]
	s_add_u32 m0, s17, 0x0
	s_nop 0
	global_load_lds_dwordx4 v141, s[0:1]
	v_mfma_f32_16x16x32_bf16 v[70:73], v[222:225], v[162:165], v[70:73]
	v_mfma_f32_16x16x32_bf16 v[74:77], v[226:229], v[162:165], v[74:77]
	s_add_u32 m0, s6, 0x4000
	s_nop 0
	global_load_lds_dwordx4 v136, s[2:3]
	v_mfma_f32_16x16x32_bf16 v[78:81], v[230:233], v[162:165], v[78:81]
	s_add_u32 m0, s6, 0x6000
	s_nop 0
	global_load_lds_dwordx4 v137, s[2:3]
	s_add_u32 s0, s0, 64
	s_addc_u32 s1, s1, 0
	s_add_u32 s2, s2, 64
	s_addc_u32 s3, s3, 0
	ds_read_b128 v[218:221], v140 offset:8192
	ds_read_b128 v[222:225], v140 offset:9216
	ds_read_b128 v[226:229], v140 offset:10240
	ds_read_b128 v[230:233], v140 offset:11264
	s_waitcnt lgkmcnt(4)
	v_mfma_f32_16x16x32_bf16 v[2:5], v[194:197], v[178:181], v[2:5]
	v_mfma_f32_16x16x32_bf16 v[6:9], v[198:201], v[178:181], v[6:9]
	v_mfma_f32_16x16x32_bf16 v[10:13], v[202:205], v[178:181], v[10:13]
	v_mfma_f32_16x16x32_bf16 v[14:17], v[206:209], v[178:181], v[14:17]
	s_waitcnt lgkmcnt(0)
	s_waitcnt vmcnt(6)
	s_barrier
	v_add_u32_e32 v139, 0x10000, v134
	v_add_u32_e32 v140, 0x10000, v135
	ds_read_b128 v[162:165], v139 offset:0
	ds_read_b128 v[194:197], v140 offset:0
	ds_read_b128 v[198:201], v140 offset:1024
	ds_read_b128 v[202:205], v140 offset:2048
	ds_read_b128 v[206:209], v140 offset:3072
	v_mfma_f32_16x16x32_bf16 v[66:69], v[218:221], v[178:181], v[66:69]
	s_add_u32 m0, s17, 0x8000
	s_nop 0
	global_load_lds_dwordx4 v141, s[0:1]
	v_mfma_f32_16x16x32_bf16 v[70:73], v[222:225], v[178:181], v[70:73]
	v_mfma_f32_16x16x32_bf16 v[74:77], v[226:229], v[178:181], v[74:77]
	s_add_u32 m0, s6, 0xc000
	s_nop 0
	global_load_lds_dwordx4 v136, s[2:3]
	v_mfma_f32_16x16x32_bf16 v[78:81], v[230:233], v[178:181], v[78:81]
	s_add_u32 m0, s6, 0xe000
	s_nop 0
	global_load_lds_dwordx4 v137, s[2:3]
	s_add_u32 s0, s0, 64
	s_addc_u32 s1, s1, 0
	s_add_u32 s2, s2, 64
	s_addc_u32 s3, s3, 0
	ds_read_b128 v[218:221], v140 offset:8192
	ds_read_b128 v[222:225], v140 offset:9216
	ds_read_b128 v[226:229], v140 offset:10240
	ds_read_b128 v[230:233], v140 offset:11264
	s_waitcnt lgkmcnt(4)
	v_mfma_f32_16x16x32_bf16 v[2:5], v[194:197], v[162:165], v[2:5]
	v_mfma_f32_16x16x32_bf16 v[6:9], v[198:201], v[162:165], v[6:9]
	v_mfma_f32_16x16x32_bf16 v[10:13], v[202:205], v[162:165], v[10:13]
	v_mfma_f32_16x16x32_bf16 v[14:17], v[206:209], v[162:165], v[14:17]
	s_waitcnt lgkmcnt(0)
	s_waitcnt vmcnt(6)
	s_barrier
	v_add_u32_e32 v139, 0x18000, v134
	v_add_u32_e32 v140, 0x18000, v135
	ds_read_b128 v[178:181], v139 offset:0
	ds_read_b128 v[194:197], v140 offset:0
	ds_read_b128 v[198:201], v140 offset:1024
	ds_read_b128 v[202:205], v140 offset:2048
	ds_read_b128 v[206:209], v140 offset:3072
	v_mfma_f32_16x16x32_bf16 v[66:69], v[218:221], v[162:165], v[66:69]
	s_add_u32 m0, s17, 0x10000
	s_nop 0
	global_load_lds_dwordx4 v141, s[0:1]
	v_mfma_f32_16x16x32_bf16 v[70:73], v[222:225], v[162:165], v[70:73]
	v_mfma_f32_16x16x32_bf16 v[74:77], v[226:229], v[162:165], v[74:77]
	s_add_u32 m0, s6, 0x14000
	s_nop 0
	global_load_lds_dwordx4 v136, s[2:3]
	v_mfma_f32_16x16x32_bf16 v[78:81], v[230:233], v[162:165], v[78:81]
	s_add_u32 m0, s6, 0x16000
	s_nop 0
	global_load_lds_dwordx4 v137, s[2:3]
	s_add_u32 s0, s0, 64
	s_addc_u32 s1, s1, 0
	s_add_u32 s2, s2, 64
	s_addc_u32 s3, s3, 0
	ds_read_b128 v[218:221], v140 offset:8192
	ds_read_b128 v[222:225], v140 offset:9216
	ds_read_b128 v[226:229], v140 offset:10240
	ds_read_b128 v[230:233], v140 offset:11264
	s_waitcnt lgkmcnt(4)
	v_mfma_f32_16x16x32_bf16 v[2:5], v[194:197], v[178:181], v[2:5]
	v_mfma_f32_16x16x32_bf16 v[6:9], v[198:201], v[178:181], v[6:9]
	v_mfma_f32_16x16x32_bf16 v[10:13], v[202:205], v[178:181], v[10:13]
	v_mfma_f32_16x16x32_bf16 v[14:17], v[206:209], v[178:181], v[14:17]
	s_waitcnt lgkmcnt(0)
	s_sub_u32 s7, s7, 1
	s_cmp_lg_u32 s7, 0
	s_cbranch_scc1 .Lg2_a_klB10
	s_waitcnt vmcnt(6)
	s_barrier
	v_add_u32_e32 v139, 0x0, v134
	v_add_u32_e32 v140, 0x0, v135
	ds_read_b128 v[162:165], v139 offset:0
	ds_read_b128 v[194:197], v140 offset:0
	ds_read_b128 v[198:201], v140 offset:1024
	ds_read_b128 v[202:205], v140 offset:2048
	ds_read_b128 v[206:209], v140 offset:3072
	v_mfma_f32_16x16x32_bf16 v[66:69], v[218:221], v[178:181], v[66:69]
	s_add_u32 m0, s17, 0x18000
	s_nop 0
	global_load_lds_dwordx4 v141, s[0:1]
	v_mfma_f32_16x16x32_bf16 v[70:73], v[222:225], v[178:181], v[70:73]
	v_mfma_f32_16x16x32_bf16 v[74:77], v[226:229], v[178:181], v[74:77]
	s_add_u32 m0, s6, 0x1c000
	s_nop 0
	global_load_lds_dwordx4 v136, s[2:3]
	v_mfma_f32_16x16x32_bf16 v[78:81], v[230:233], v[178:181], v[78:81]
	s_add_u32 m0, s6, 0x1e000
	s_nop 0
	global_load_lds_dwordx4 v137, s[2:3]
	s_add_u32 s0, s0, 64
	s_addc_u32 s1, s1, 0
	s_add_u32 s2, s2, 64
	s_addc_u32 s3, s3, 0
	ds_read_b128 v[218:221], v140 offset:8192
	ds_read_b128 v[222:225], v140 offset:9216
	ds_read_b128 v[226:229], v140 offset:10240
	ds_read_b128 v[230:233], v140 offset:11264
	s_waitcnt lgkmcnt(4)
	v_mfma_f32_16x16x32_bf16 v[2:5], v[194:197], v[162:165], v[2:5]
	v_mfma_f32_16x16x32_bf16 v[6:9], v[198:201], v[162:165], v[6:9]
	v_mfma_f32_16x16x32_bf16 v[10:13], v[202:205], v[162:165], v[10:13]
	v_mfma_f32_16x16x32_bf16 v[14:17], v[206:209], v[162:165], v[14:17]
	s_waitcnt lgkmcnt(0)
	s_waitcnt vmcnt(6)
	s_barrier
	v_add_u32_e32 v139, 0x8000, v134
	v_add_u32_e32 v140, 0x8000, v135
	ds_read_b128 v[178:181], v139 offset:0
	ds_read_b128 v[194:197], v140 offset:0
	ds_read_b128 v[198:201], v140 offset:1024
	ds_read_b128 v[202:205], v140 offset:2048
	ds_read_b128 v[206:209], v140 offset:3072
	v_mfma_f32_16x16x32_bf16 v[66:69], v[218:221], v[162:165], v[66:69]
	v_mfma_f32_16x16x32_bf16 v[70:73], v[222:225], v[162:165], v[70:73]
	v_mfma_f32_16x16x32_bf16 v[74:77], v[226:229], v[162:165], v[74:77]
	v_mfma_f32_16x16x32_bf16 v[78:81], v[230:233], v[162:165], v[78:81]
	ds_read_b128 v[218:221], v140 offset:8192
	ds_read_b128 v[222:225], v140 offset:9216
	ds_read_b128 v[226:229], v140 offset:10240
	ds_read_b128 v[230:233], v140 offset:11264
	s_waitcnt lgkmcnt(4)
	v_mfma_f32_16x16x32_bf16 v[2:5], v[194:197], v[178:181], v[2:5]
	v_mfma_f32_16x16x32_bf16 v[6:9], v[198:201], v[178:181], v[6:9]
	v_mfma_f32_16x16x32_bf16 v[10:13], v[202:205], v[178:181], v[10:13]
	v_mfma_f32_16x16x32_bf16 v[14:17], v[206:209], v[178:181], v[14:17]
	s_waitcnt lgkmcnt(0)
	s_waitcnt vmcnt(3)
	s_barrier
	v_add_u32_e32 v139, 0x10000, v134
	v_add_u32_e32 v140, 0x10000, v135
	ds_read_b128 v[162:165], v139 offset:0
	ds_read_b128 v[194:197], v140 offset:0
	ds_read_b128 v[198:201], v140 offset:1024
	ds_read_b128 v[202:205], v140 offset:2048
	ds_read_b128 v[206:209], v140 offset:3072
	v_mfma_f32_16x16x32_bf16 v[66:69], v[218:221], v[178:181], v[66:69]
	v_mfma_f32_16x16x32_bf16 v[70:73], v[222:225], v[178:181], v[70:73]
	v_mfma_f32_16x16x32_bf16 v[74:77], v[226:229], v[178:181], v[74:77]
	v_mfma_f32_16x16x32_bf16 v[78:81], v[230:233], v[178:181], v[78:81]
	ds_read_b128 v[218:221], v140 offset:8192
	ds_read_b128 v[222:225], v140 offset:9216
	ds_read_b128 v[226:229], v140 offset:10240
	ds_read_b128 v[230:233], v140 offset:11264
	s_waitcnt lgkmcnt(4)
	v_mfma_f32_16x16x32_bf16 v[2:5], v[194:197], v[162:165], v[2:5]
	v_mfma_f32_16x16x32_bf16 v[6:9], v[198:201], v[162:165], v[6:9]
	v_mfma_f32_16x16x32_bf16 v[10:13], v[202:205], v[162:165], v[10:13]
	v_mfma_f32_16x16x32_bf16 v[14:17], v[206:209], v[162:165], v[14:17]
	s_waitcnt lgkmcnt(0)
	s_waitcnt vmcnt(0)
	s_barrier
	v_add_u32_e32 v139, 0x18000, v134
	v_add_u32_e32 v140, 0x18000, v135
	ds_read_b128 v[178:181], v139 offset:0
	ds_read_b128 v[194:197], v140 offset:0
	ds_read_b128 v[198:201], v140 offset:1024
	ds_read_b128 v[202:205], v140 offset:2048
	ds_read_b128 v[206:209], v140 offset:3072
	v_mfma_f32_16x16x32_bf16 v[66:69], v[218:221], v[162:165], v[66:69]
	v_mfma_f32_16x16x32_bf16 v[70:73], v[222:225], v[162:165], v[70:73]
	v_mfma_f32_16x16x32_bf16 v[74:77], v[226:229], v[162:165], v[74:77]
	v_mfma_f32_16x16x32_bf16 v[78:81], v[230:233], v[162:165], v[78:81]
	ds_read_b128 v[218:221], v140 offset:8192
	ds_read_b128 v[222:225], v140 offset:9216
	ds_read_b128 v[226:229], v140 offset:10240
	ds_read_b128 v[230:233], v140 offset:11264
	s_waitcnt lgkmcnt(4)
	v_mfma_f32_16x16x32_bf16 v[2:5], v[194:197], v[178:181], v[2:5]
	v_mfma_f32_16x16x32_bf16 v[6:9], v[198:201], v[178:181], v[6:9]
	v_mfma_f32_16x16x32_bf16 v[10:13], v[202:205], v[178:181], v[10:13]
	v_mfma_f32_16x16x32_bf16 v[14:17], v[206:209], v[178:181], v[14:17]
	s_waitcnt lgkmcnt(0)
	v_mfma_f32_16x16x32_bf16 v[66:69], v[218:221], v[178:181], v[66:69]
	v_mfma_f32_16x16x32_bf16 v[70:73], v[222:225], v[178:181], v[70:73]
	v_mfma_f32_16x16x32_bf16 v[74:77], v[226:229], v[178:181], v[74:77]
	v_mfma_f32_16x16x32_bf16 v[78:81], v[230:233], v[178:181], v[78:81]
.Lg2_a_kdone8:
	s_nop 7
	s_nop 1
	v_mov_b32_e32 v242, v138
	v_mul_f32_e32 v234, 0xbfb8aa3b, v2
	v_mul_f32_e32 v235, 0xbfb8aa3b, v3
	v_mul_f32_e32 v236, 0xbfb8aa3b, v4
	v_mul_f32_e32 v237, 0xbfb8aa3b, v5
	v_exp_f32_e32 v234, v234
	v_exp_f32_e32 v235, v235
	v_exp_f32_e32 v236, v236
	v_exp_f32_e32 v237, v237
	v_add_f32_e32 v234, 1.0, v234
	v_add_f32_e32 v235, 1.0, v235
	v_add_f32_e32 v236, 1.0, v236
	v_add_f32_e32 v237, 1.0, v237
	v_rcp_f32_e32 v234, v234
	v_rcp_f32_e32 v235, v235
	v_rcp_f32_e32 v236, v236
	v_rcp_f32_e32 v237, v237
	v_mul_f32_e32 v234, v2, v234
	v_mul_f32_e32 v235, v3, v235
	v_mul_f32_e32 v236, v4, v236
	v_mul_f32_e32 v237, v5, v237
	v_mul_f32_e32 v234, v10, v234
	v_mul_f32_e32 v235, v11, v235
	v_mul_f32_e32 v236, v12, v236
	v_mul_f32_e32 v237, v13, v237
	v_cvt_pk_bf16_f32 v238, v234, v235
	v_cvt_pk_bf16_f32 v239, v236, v237
	global_store_dwordx2 v242, v[238:239], s[4:5] offset:0
	v_mul_f32_e32 v234, 0xbfb8aa3b, v6
	v_mul_f32_e32 v235, 0xbfb8aa3b, v7
	v_mul_f32_e32 v236, 0xbfb8aa3b, v8
	v_mul_f32_e32 v237, 0xbfb8aa3b, v9
	v_exp_f32_e32 v234, v234
	v_exp_f32_e32 v235, v235
	v_exp_f32_e32 v236, v236
	v_exp_f32_e32 v237, v237
	v_add_f32_e32 v234, 1.0, v234
	v_add_f32_e32 v235, 1.0, v235
	v_add_f32_e32 v236, 1.0, v236
	v_add_f32_e32 v237, 1.0, v237
	v_rcp_f32_e32 v234, v234
	v_rcp_f32_e32 v235, v235
	v_rcp_f32_e32 v236, v236
	v_rcp_f32_e32 v237, v237
	v_mul_f32_e32 v234, v6, v234
	v_mul_f32_e32 v235, v7, v235
	v_mul_f32_e32 v236, v8, v236
	v_mul_f32_e32 v237, v9, v237
	v_mul_f32_e32 v234, v14, v234
	v_mul_f32_e32 v235, v15, v235
	v_mul_f32_e32 v236, v16, v236
	v_mul_f32_e32 v237, v17, v237
	v_cvt_pk_bf16_f32 v240, v234, v235
	v_cvt_pk_bf16_f32 v241, v236, v237
	global_store_dwordx2 v242, v[240:241], s[4:5] offset:32
	v_mul_f32_e32 v234, 0xbfb8aa3b, v66
	v_mul_f32_e32 v235, 0xbfb8aa3b, v67
	v_mul_f32_e32 v236, 0xbfb8aa3b, v68
	v_mul_f32_e32 v237, 0xbfb8aa3b, v69
	v_exp_f32_e32 v234, v234
	v_exp_f32_e32 v235, v235
	v_exp_f32_e32 v236, v236
	v_exp_f32_e32 v237, v237
	v_add_f32_e32 v234, 1.0, v234
	v_add_f32_e32 v235, 1.0, v235
	v_add_f32_e32 v236, 1.0, v236
	v_add_f32_e32 v237, 1.0, v237
	v_rcp_f32_e32 v234, v234
	v_rcp_f32_e32 v235, v235
	v_rcp_f32_e32 v236, v236
	v_rcp_f32_e32 v237, v237
	v_mul_f32_e32 v234, v66, v234
	v_mul_f32_e32 v235, v67, v235
	v_mul_f32_e32 v236, v68, v236
	v_mul_f32_e32 v237, v69, v237
	v_mul_f32_e32 v234, v74, v234
	v_mul_f32_e32 v235, v75, v235
	v_mul_f32_e32 v236, v76, v236
	v_mul_f32_e32 v237, v77, v237
	v_cvt_pk_bf16_f32 v238, v234, v235
	v_cvt_pk_bf16_f32 v239, v236, v237
	global_store_dwordx2 v242, v[238:239], s[4:5] offset:128
	v_mul_f32_e32 v234, 0xbfb8aa3b, v70
	v_mul_f32_e32 v235, 0xbfb8aa3b, v71
	v_mul_f32_e32 v236, 0xbfb8aa3b, v72
	v_mul_f32_e32 v237, 0xbfb8aa3b, v73
	v_exp_f32_e32 v234, v234
	v_exp_f32_e32 v235, v235
	v_exp_f32_e32 v236, v236
	v_exp_f32_e32 v237, v237
	v_add_f32_e32 v234, 1.0, v234
	v_add_f32_e32 v235, 1.0, v235
	v_add_f32_e32 v236, 1.0, v236
	v_add_f32_e32 v237, 1.0, v237
	v_rcp_f32_e32 v234, v234
	v_rcp_f32_e32 v235, v235
	v_rcp_f32_e32 v236, v236
	v_rcp_f32_e32 v237, v237
	v_mul_f32_e32 v234, v70, v234
	v_mul_f32_e32 v235, v71, v235
	v_mul_f32_e32 v236, v72, v236
	v_mul_f32_e32 v237, v73, v237
	v_mul_f32_e32 v234, v78, v234
	v_mul_f32_e32 v235, v79, v235
	v_mul_f32_e32 v236, v80, v236
	v_mul_f32_e32 v237, v81, v237
	v_cvt_pk_bf16_f32 v240, v234, v235
	v_cvt_pk_bf16_f32 v241, v236, v237
	global_store_dwordx2 v242, v[240:241], s[4:5] offset:160
.Lg2_a_noleft6:
	s_branch .LBB0_70
.LBB0_57:
	s_mov_b64 s[2:3], 0
	v_writelane_b32 v214, s2, 59
	s_nop 1
	v_writelane_b32 v214, s3, 60
	s_and_b64 vcc, exec, s[0:1]
	s_cbranch_vccnz .LBB0_103
	s_branch .LBB0_166

.LBB0_59:
	s_mov_b64 s[2:3], 0
	v_writelane_b32 v214, s2, 59
	s_nop 1
	v_writelane_b32 v214, s3, 60
	s_and_b64 vcc, exec, s[0:1]
	s_cbranch_vccnz .LBB0_72
	s_branch .LBB0_96
.LBB0_70:
	v_readlane_b32 s8, v217, 20
	s_mov_b64 s[44:45], 0x100
	s_mov_b64 s[0:1], 0
	v_readlane_b32 s9, v217, 21

.LBB0_405:
	s_andn2_b64 vcc, exec, s[0:1]
	s_mov_b64 s[2:3], 0
	s_cbranch_vccnz .LBB0_417
	s_cmp_gt_i32 s21, 0
	s_mov_b64 s[0:1], -1
	s_cbranch_scc0 .LBB0_429
	v_readlane_b32 s11, v217, 0
	v_readlane_b32 s12, v214, 57
	s_and_b32 s14, s11, 7
	s_lshr_b32 s15, s11, 3
	s_mul_hi_u32 s16, s12, 0x3500000
	s_mul_i32 s12, s12, 0x3500000
	s_add_u32 s40, s48, s12
	s_addc_u32 s41, s49, s16
	s_add_u32 s40, s40, 0xf5ce000
	s_addc_u32 s41, s41, 0
	v_and_b32_e32 v141, 15, v142
	v_lshrrev_b32_e32 v139, 4, v142
	v_and_b32_e32 v139, 3, v139
	v_lshlrev_b32_e32 v140, 6, v141
	v_lshl_add_u32 v140, v139, 4, v140
	v_lshrrev_b32_e32 v139, 3, v141
	v_lshlrev_b32_e32 v139, 5, v139
	v_xor_b32_e32 v135, v140, v139
	v_lshrrev_b32_e32 v139, 7, v142
	v_lshl_add_u32 v134, v139, 12, v135
	v_lshrrev_b32_e32 v139, 6, v142
	v_and_b32_e32 v139, 1, v139
	v_lshl_add_u32 v135, v139, 12, v135
	v_add_u32_e32 v135, 0x4000, v135
	v_and_b32_e32 v141, 63, v142
	v_lshrrev_b32_e32 v139, 2, v141
	v_lshrrev_b32_e32 v140, 6, v142
	v_lshl_add_u32 v139, v140, 4, v139
	v_lshlrev_b32_e32 v139, 11, v139
	v_and_b32_e32 v140, 3, v141
	v_lshlrev_b32_e32 v140, 4, v140
	v_lshrrev_b32_e32 v141, 5, v141
	v_lshlrev_b32_e32 v141, 5, v141
	v_xor_b32_e32 v140, v140, v141
	v_add_u32_e32 v136, v139, v140
	v_add_u32_e32 v137, 0x40000, v136
	v_lshrrev_b32_e32 v139, 7, v142
	v_and_b32_e32 v141, 15, v142
	v_lshl_add_u32 v139, v139, 6, v141
	v_mul_u32_u24_e32 v139, 0x1600, v139
	v_lshrrev_b32_e32 v140, 6, v142
	v_and_b32_e32 v140, 1, v140
	v_lshlrev_b32_e32 v140, 6, v140
	v_lshrrev_b32_e32 v141, 4, v142
	v_and_b32_e32 v141, 3, v141
	v_lshl_add_u32 v140, v141, 3, v140
	v_add_u32_e32 v138, v139, v140
	v_lshrrev_b32_e32 v141, 6, v142
	v_lshlrev_b32_e32 v141, 10, v141
	s_nop 0
	v_readfirstlane_b32 s6, v141
	s_mov_b32 s10, s15

.Lg2_b_noleft6:
	s_branch .LBB0_428
.LBB0_417:
	v_readlane_b32 s0, v214, 59
	v_readlane_b32 s1, v214, 60
	s_branch .LBB0_431
.LBB0_428:
	s_mov_b64 s[0:1], 0

	.amdhsa_kernel _Z10fwd_kernel6Params
		.amdhsa_group_segment_fixed_size 0
		.amdhsa_private_segment_fixed_size 0
		.amdhsa_kernarg_size 464
		.amdhsa_user_sgpr_count 2
		.amdhsa_user_sgpr_dispatch_ptr 0
		.amdhsa_user_sgpr_queue_ptr 0
		.amdhsa_user_sgpr_kernarg_segment_ptr 1
		.amdhsa_user_sgpr_dispatch_id 0
		.amdhsa_user_sgpr_kernarg_preload_length 0
		.amdhsa_user_sgpr_kernarg_preload_offset 0
		.amdhsa_user_sgpr_private_segment_size 0
		.amdhsa_uses_dynamic_stack 0
		.amdhsa_enable_private_segment 0
		.amdhsa_system_sgpr_workgroup_id_x 1
		.amdhsa_system_sgpr_workgroup_id_y 0
		.amdhsa_system_sgpr_workgroup_id_z 0
		.amdhsa_system_sgpr_workgroup_info 0
		.amdhsa_system_vgpr_workitem_id 2
		.amdhsa_next_free_vgpr 244
		.amdhsa_next_free_sgpr 100
		.amdhsa_accum_offset 244
		.amdhsa_reserve_vcc 1
		.amdhsa_float_round_mode_32 0
		.amdhsa_float_round_mode_16_64 0
		.amdhsa_float_denorm_mode_32 3
		.amdhsa_float_denorm_mode_16_64 3
		.amdhsa_dx10_clamp 1
		.amdhsa_ieee_mode 1
		.amdhsa_fp16_overflow 0
		.amdhsa_tg_split 0
		.amdhsa_exception_fp_ieee_invalid_op 0
		.amdhsa_exception_fp_denorm_src 0
		.amdhsa_exception_fp_ieee_div_zero 0
		.amdhsa_exception_fp_ieee_overflow 0
		.amdhsa_exception_fp_ieee_underflow 0
		.amdhsa_exception_fp_ieee_inexact 0
		.amdhsa_exception_int_div_zero 0
	.end_amdhsa_kernel

.Lfunc_end0:
	.size	_Z10fwd_kernel6Params, .Lfunc_end0-_Z10fwd_kernel6Params
	.set _Z10fwd_kernel6Params.num_vgpr, 244
	.set _Z10fwd_kernel6Params.num_agpr, 0
	.set _Z10fwd_kernel6Params.numbered_sgpr, 100
	.set _Z10fwd_kernel6Params.num_named_barrier, 0
	.set _Z10fwd_kernel6Params.private_seg_size, 0
	.set _Z10fwd_kernel6Params.uses_vcc, 1
	.set _Z10fwd_kernel6Params.uses_flat_scratch, 0
	.set _Z10fwd_kernel6Params.has_dyn_sized_stack, 0
	.set _Z10fwd_kernel6Params.has_recursion, 0
	.set _Z10fwd_kernel6Params.has_indirect_call, 0

amdhsa.kernels:
  - .agpr_count:     0
    .args:
      - .offset:         0
        .size:           208
        .value_kind:     by_value
      - .offset:         208
        .size:           4
        .value_kind:     hidden_block_count_x
      - .offset:         212
        .size:           4
        .value_kind:     hidden_block_count_y
      - .offset:         216
        .size:           4
        .value_kind:     hidden_block_count_z
      - .offset:         220
        .size:           2
        .value_kind:     hidden_group_size_x
      - .offset:         222
        .size:           2
        .value_kind:     hidden_group_size_y
      - .offset:         224
        .size:           2
        .value_kind:     hidden_group_size_z
      - .offset:         226
        .size:           2
        .value_kind:     hidden_remainder_x
      - .offset:         228
        .size:           2
        .value_kind:     hidden_remainder_y
      - .offset:         230
        .size:           2
        .value_kind:     hidden_remainder_z
      - .offset:         248
        .size:           8
        .value_kind:     hidden_global_offset_x
      - .offset:         256
        .size:           8
        .value_kind:     hidden_global_offset_y
      - .offset:         264
        .size:           8
        .value_kind:     hidden_global_offset_z
      - .offset:         272
        .size:           2
        .value_kind:     hidden_grid_dims
      - .offset:         296
        .size:           8
        .value_kind:     hidden_multigrid_sync_arg
      - .offset:         328
        .size:           4
        .value_kind:     hidden_dynamic_lds_size
    .group_segment_fixed_size: 0
    .kernarg_segment_align: 8
    .kernarg_segment_size: 464
    .language:       OpenCL C
    .language_version:
      - 2
      - 0
    .max_flat_workgroup_size: 512
    .name:           _Z10fwd_kernel6Params
    .private_segment_fixed_size: 0
    .sgpr_count:     106
    .sgpr_spill_count: 265
    .symbol:         _Z10fwd_kernel6Params.kd
    .uniform_work_group_size: 1
    .uses_dynamic_stack: false
    .vgpr_count:     244
    .vgpr_spill_count: 0
    .wavefront_size: 64
